# LRU items: redundant workgroup barrier between conv and gate GEMM removed (ucb rows are written and read by the same wave; in-order LDS + lgkmcnt(0) suffices)
# baseline (speedup 1.0000x reference)
; DEVI unsigned pk2(float lo, float hi) { f32x2 v = {lo, hi}; bf16x2_t b = __builtin_convertvector(v, bf16x2_t); return __builtin_bit_cast(unsigned, b); }
; DEVI float bflo(unsigned u) { return __uint_as_float(u << 16); }
; DEVI float bfhi(unsigned u) { return __uint_as_float(u & 0xffff0000u); }
; template <bool PASS_C>
; DEVI void lru_item(const P& p, int item, int next_item, uint4& u0, uint4& u1, uint4& u2, float& cpre, char* smem) {
;     ...
;     {
;         const int tok = tid >> 2, cg0 = (tid & 3) * 16;
;         uint4 r[4][2];
; #pragma unroll
;         for (int k = 0; k < 4; ++k) { r[k][0] = *(const uint4*)(us + (tok + k) * 64 + cg0); r[k][1] = *(const uint4*)(us + (tok + k) * 64 + cg0 + 8); }
;         float val[16];
; #pragma unroll
;         for (int e = 0; e < 16; ++e) {
;             const int ch = cg0 + e;
;             float a = prm[4 * 64 + ch];
; #pragma unroll
;             for (int k = 0; k < 4; ++k) {
;                 const uint4 q = r[k][e >> 3];
;                 const unsigned wd = ((e >> 1) & 3) == 0 ? q.x : (((e >> 1) & 3) == 1 ? q.y : (((e >> 1) & 3) == 2 ? q.z : q.w));
;                 a += prm[k * 64 + ch] * ((e & 1) ? bfhi(wd) : bflo(wd));
;             }
;             val[e] = a;
;         }
;         uint4 o;
;         o.x = pk2(val[0], val[1]); o.y = pk2(val[2], val[3]); o.z = pk2(val[4], val[5]); o.w = pk2(val[6], val[7]);
;         *(uint4*)(ucb + tok * 128 + ((((cg0 >> 3) + 0) ^ (tok & 7)) << 4)) = o;
;         o.x = pk2(val[8], val[9]); o.y = pk2(val[10], val[11]); o.z = pk2(val[12], val[13]); o.w = pk2(val[14], val[15]);
;         *(uint4*)(ucb + tok * 128 + ((((cg0 >> 3) + 1) ^ (tok & 7)) << 4)) = o;
;     }
.LBB0_510:
	s_waitcnt lgkmcnt(0)
	s_barrier
	ds_read_b128 v[32:35], v118 offset:35840
	ds_read_b128 v[12:15], v118 offset:35856
	ds_read_b128 v[36:39], v118 offset:35968
	ds_read_b128 v[16:19], v118 offset:35984
	ds_read_b128 v[40:43], v118 offset:36096
	ds_read_b128 v[20:23], v118 offset:36112
	ds_read_b128 v[44:47], v118 offset:36224
	ds_read_b128 v[24:27], v118 offset:36240
	ds_read_b128 v[48:51], v111 offset:33792
	ds_read_b128 v[52:55], v111 offset:32768
	ds_read_b128 v[56:59], v111 offset:32784
	ds_read_b128 v[60:63], v111 offset:32800
	ds_read_b128 v[28:31], v111 offset:32816
	ds_read_b128 v[64:67], v111 offset:33024
	ds_read_b128 v[92:95], v111 offset:33808
	s_waitcnt lgkmcnt(14)
	v_lshlrev_b32_e32 v96, 16, v32
	v_and_b32_e32 v97, 0xffff0000, v32
	s_waitcnt lgkmcnt(5)
	v_pk_fma_f32 v[48:49], v[52:53], v[96:97], v[48:49]
	ds_read_b128 v[96:99], v111 offset:33280
	ds_read_b128 v[146:149], v111 offset:33536
	ds_read_b128 v[150:153], v111 offset:33040
	v_lshlrev_b32_e32 v32, 16, v33
	v_and_b32_e32 v33, 0xffff0000, v33
	v_lshlrev_b32_e32 v154, 16, v36
	v_and_b32_e32 v155, 0xffff0000, v36
	v_lshlrev_b32_e32 v36, 16, v37
	v_and_b32_e32 v37, 0xffff0000, v37
	v_pk_fma_f32 v[32:33], v[54:55], v[32:33], v[50:51]
	v_lshlrev_b32_e32 v158, 16, v40
	v_and_b32_e32 v159, 0xffff0000, v40
	s_waitcnt lgkmcnt(4)
	v_pk_fma_f32 v[48:49], v[64:65], v[154:155], v[48:49]
	ds_read_b128 v[154:157], v111 offset:33296
	v_lshlrev_b32_e32 v40, 16, v41
	v_and_b32_e32 v41, 0xffff0000, v41
	v_pk_fma_f32 v[32:33], v[66:67], v[36:37], v[32:33]
	v_lshlrev_b32_e32 v162, 16, v44
	v_and_b32_e32 v163, 0xffff0000, v44
	s_waitcnt lgkmcnt(3)
	v_pk_fma_f32 v[48:49], v[96:97], v[158:159], v[48:49]
	ds_read_b128 v[158:161], v111 offset:33552
	v_lshlrev_b32_e32 v44, 16, v45
	v_and_b32_e32 v45, 0xffff0000, v45
	v_pk_fma_f32 v[32:33], v[98:99], v[40:41], v[32:33]
	v_lshlrev_b32_e32 v36, 16, v38
	s_waitcnt lgkmcnt(3)
	v_pk_fma_f32 v[98:99], v[148:149], v[44:45], v[32:33]
	v_lshlrev_b32_e32 v32, 16, v34
	v_and_b32_e32 v33, 0xffff0000, v34
	v_and_b32_e32 v37, 0xffff0000, v38
	v_pk_fma_f32 v[32:33], v[56:57], v[32:33], v[92:93]
	v_lshlrev_b32_e32 v40, 16, v42
	v_and_b32_e32 v41, 0xffff0000, v42
	s_waitcnt lgkmcnt(2)
	v_pk_fma_f32 v[32:33], v[150:151], v[36:37], v[32:33]
	v_lshlrev_b32_e32 v44, 16, v46
	v_and_b32_e32 v45, 0xffff0000, v46
	s_waitcnt lgkmcnt(1)
	v_pk_fma_f32 v[32:33], v[154:155], v[40:41], v[32:33]
	v_lshlrev_b32_e32 v34, 16, v39
	s_waitcnt lgkmcnt(0)
	v_pk_fma_f32 v[92:93], v[158:159], v[44:45], v[32:33]
	v_lshlrev_b32_e32 v32, 16, v35
	v_and_b32_e32 v33, 0xffff0000, v35
	v_and_b32_e32 v35, 0xffff0000, v39
	v_pk_fma_f32 v[32:33], v[58:59], v[32:33], v[94:95]
	v_lshlrev_b32_e32 v36, 16, v43
	v_and_b32_e32 v37, 0xffff0000, v43
	v_pk_fma_f32 v[32:33], v[152:153], v[34:35], v[32:33]
	v_lshlrev_b32_e32 v38, 16, v47
	v_and_b32_e32 v39, 0xffff0000, v47
	v_pk_fma_f32 v[32:33], v[156:157], v[36:37], v[32:33]
	v_lshlrev_b32_e32 v44, 16, v12
	v_pk_fma_f32 v[94:95], v[160:161], v[38:39], v[32:33]
	ds_read_b128 v[32:35], v111 offset:33824
	ds_read_b128 v[36:39], v111 offset:33056
	ds_read_b128 v[40:43], v111 offset:33840
	v_and_b32_e32 v45, 0xffff0000, v12
	v_pk_fma_f32 v[96:97], v[146:147], v[162:163], v[48:49]
	v_lshlrev_b32_e32 v12, 16, v13
	s_waitcnt lgkmcnt(2)
	v_pk_fma_f32 v[32:33], v[60:61], v[44:45], v[32:33]
	ds_read_b128 v[44:47], v111 offset:33312
	ds_read_b128 v[48:51], v111 offset:33568
	ds_read_b128 v[52:55], v111 offset:33072
	v_and_b32_e32 v13, 0xffff0000, v13
	v_lshlrev_b32_e32 v56, 16, v16
	v_and_b32_e32 v57, 0xffff0000, v16
	v_lshlrev_b32_e32 v16, 16, v17
	v_and_b32_e32 v17, 0xffff0000, v17
	v_pk_fma_f32 v[12:13], v[62:63], v[12:13], v[34:35]
	v_lshlrev_b32_e32 v64, 16, v20
	v_and_b32_e32 v65, 0xffff0000, v20
	s_waitcnt lgkmcnt(4)
	v_pk_fma_f32 v[32:33], v[36:37], v[56:57], v[32:33]
	ds_read_b128 v[56:59], v111 offset:33328
	v_lshlrev_b32_e32 v20, 16, v21
	v_and_b32_e32 v21, 0xffff0000, v21
	v_pk_fma_f32 v[12:13], v[38:39], v[16:17], v[12:13]
	v_lshlrev_b32_e32 v146, 16, v24
	v_and_b32_e32 v147, 0xffff0000, v24
	s_waitcnt lgkmcnt(3)
	v_pk_fma_f32 v[32:33], v[44:45], v[64:65], v[32:33]
	ds_read_b128 v[64:67], v111 offset:33584
	v_lshlrev_b32_e32 v24, 16, v25
	v_and_b32_e32 v25, 0xffff0000, v25
	v_pk_fma_f32 v[12:13], v[46:47], v[20:21], v[12:13]
	v_lshlrev_b32_e32 v20, 16, v18
	s_waitcnt lgkmcnt(3)
	v_pk_fma_f32 v[16:17], v[50:51], v[24:25], v[12:13]
	v_lshlrev_b32_e32 v12, 16, v14
	v_and_b32_e32 v13, 0xffff0000, v14
	v_and_b32_e32 v21, 0xffff0000, v18
	v_pk_fma_f32 v[12:13], v[28:29], v[12:13], v[40:41]
	v_lshlrev_b32_e32 v24, 16, v22
	v_and_b32_e32 v25, 0xffff0000, v22
	s_waitcnt lgkmcnt(2)
	v_pk_fma_f32 v[12:13], v[52:53], v[20:21], v[12:13]
	v_lshlrev_b32_e32 v34, 16, v26
	v_and_b32_e32 v35, 0xffff0000, v26
	s_waitcnt lgkmcnt(1)
	v_pk_fma_f32 v[12:13], v[56:57], v[24:25], v[12:13]
	v_lshlrev_b32_e32 v14, 16, v19
	s_waitcnt lgkmcnt(0)
	v_pk_fma_f32 v[20:21], v[64:65], v[34:35], v[12:13]
	v_lshlrev_b32_e32 v12, 16, v15
	v_and_b32_e32 v13, 0xffff0000, v15
	v_and_b32_e32 v15, 0xffff0000, v19
	v_pk_fma_f32 v[12:13], v[30:31], v[12:13], v[42:43]
	v_lshlrev_b32_e32 v18, 16, v23
	v_and_b32_e32 v19, 0xffff0000, v23
	v_pk_fma_f32 v[12:13], v[54:55], v[14:15], v[12:13]
	v_lshlrev_b32_e32 v22, 16, v27
	v_and_b32_e32 v23, 0xffff0000, v27
	v_pk_fma_f32 v[12:13], v[58:59], v[18:19], v[12:13]
	v_pk_fma_f32 v[32:33], v[48:49], v[146:147], v[32:33]
	v_pk_fma_f32 v[18:19], v[66:67], v[22:23], v[12:13]
	v_cvt_pk_bf16_f32 v12, v96, v97
	v_cvt_pk_bf16_f32 v13, v98, v99
	v_cvt_pk_bf16_f32 v14, v92, v93
	v_cvt_pk_bf16_f32 v15, v94, v95
	ds_write_b128 v119, v[12:15] offset:44544
	v_cvt_pk_bf16_f32 v12, v32, v33
	v_cvt_pk_bf16_f32 v13, v16, v17
	v_cvt_pk_bf16_f32 v14, v20, v21
	v_cvt_pk_bf16_f32 v15, v18, v19
	ds_write_b128 v120, v[12:15] offset:44544
	v_add_u32_e32 v12, v113, v114
	s_waitcnt lgkmcnt(0)
; template <bool PASS_C>
; DEVI void lru_item(const P& p, int item, int next_item, uint4& u0, uint4& u1, uint4& u2, float& cpre, char* smem) {
;     ...
;     f32x4 acc[16];
; #pragma unroll
;     for (int n = 0; n < 16; ++n) acc[n] = (f32x4){0.f, 0.f, 0.f, 0.f};
;     {
;         bf16x8 af[2];
; #pragma unroll
;         for (int kk = 0; kk < 2; ++kk) af[kk] = *(const bf16x8*)(ucb + (16 * w + fr) * 128 + (((kk * 4 + fq) ^ (fr & 7)) << 4));
; #pragma unroll
;         for (int n = 0; n < 16; ++n)
; #pragma unroll
;             for (int kk = 0; kk < 2; ++kk) {
;                 const bf16x8 bfr = *(const bf16x8*)(smem + (16 * n + fr) * 128 + (((kk * 4 + fq) ^ (fr & 7)) << 4));
;                 acc[n] = __builtin_amdgcn_mfma_f32_16x16x32_bf16(af[kk], bfr, acc[n], 0, 0, 0);
;             }
;     }
	v_add_u32_e32 v75, v112, v114
	v_add_u32_e32 v20, v113, v115
	v_add_u32_e32 v77, v112, v115
	ds_read_b128 v[12:15], v12 offset:44544
	ds_read_b128 v[92:95], v20 offset:44544
	ds_read_b32 v83, v116 offset:35072
	ds_read_b128 v[232:235], v75
	ds_read_b128 v[236:239], v77
	ds_read_b128 v[240:243], v75 offset:2048
	ds_read_b128 v[244:247], v77 offset:2048
	ds_read_b128 v[248:251], v75 offset:4096
	ds_read_b128 v[158:161], v77 offset:4096
	ds_read_b128 v[252:255], v75 offset:6144
	ds_read_b128 v[218:221], v77 offset:6144
	s_waitcnt lgkmcnt(4)
	v_mfma_f32_16x16x32_bf16 v[146:149], v[12:15], v[232:235], 0
	ds_read_b128 v[222:225], v75 offset:8192
	ds_read_b128 v[226:229], v77 offset:8192
	ds_read_b128 v[96:99], v75 offset:10240
	ds_read_b128 v[154:157], v77 offset:10240
	v_mfma_f32_16x16x32_bf16 v[56:59], v[12:15], v[240:243], 0
	v_mfma_f32_16x16x32_bf16 v[146:149], v[92:95], v[236:239], v[146:149]
	v_mfma_f32_16x16x32_bf16 v[56:59], v[92:95], v[244:247], v[56:59]
	s_waitcnt lgkmcnt(4)
	v_mfma_f32_16x16x32_bf16 v[40:43], v[12:15], v[248:251], 0
	ds_read_b128 v[232:235], v75 offset:12288
	ds_read_b128 v[236:239], v77 offset:12288
	ds_read_b128 v[240:243], v75 offset:14336
	ds_read_b128 v[244:247], v77 offset:14336
	v_mfma_f32_16x16x32_bf16 v[24:27], v[12:15], v[252:255], 0
	v_mfma_f32_16x16x32_bf16 v[40:43], v[92:95], v[158:161], v[40:43]
	v_mfma_f32_16x16x32_bf16 v[24:27], v[92:95], v[218:221], v[24:27]
	s_waitcnt lgkmcnt(4)
	v_mfma_f32_16x16x32_bf16 v[150:153], v[12:15], v[222:225], 0
	ds_read_b128 v[248:251], v75 offset:16384
	ds_read_b128 v[158:161], v77 offset:16384
	ds_read_b128 v[252:255], v75 offset:18432
	ds_read_b128 v[218:221], v77 offset:18432
	v_mfma_f32_16x16x32_bf16 v[52:55], v[12:15], v[96:99], 0
	v_mfma_f32_16x16x32_bf16 v[150:153], v[92:95], v[226:229], v[150:153]
	v_mfma_f32_16x16x32_bf16 v[52:55], v[92:95], v[154:157], v[52:55]
	s_waitcnt lgkmcnt(4)
	v_mfma_f32_16x16x32_bf16 v[36:39], v[12:15], v[232:235], 0
	ds_read_b128 v[222:225], v75 offset:20480
	ds_read_b128 v[226:229], v77 offset:20480
	ds_read_b128 v[96:99], v75 offset:22528
	ds_read_b128 v[154:157], v77 offset:22528
	v_mfma_f32_16x16x32_bf16 v[20:23], v[12:15], v[240:243], 0
	v_mfma_f32_16x16x32_bf16 v[36:39], v[92:95], v[236:239], v[36:39]
	v_mfma_f32_16x16x32_bf16 v[20:23], v[92:95], v[244:247], v[20:23]
	s_waitcnt lgkmcnt(4)
	v_mfma_f32_16x16x32_bf16 v[64:67], v[12:15], v[248:251], 0
	ds_read_b128 v[232:235], v75 offset:24576
	ds_read_b128 v[236:239], v77 offset:24576
	ds_read_b128 v[240:243], v75 offset:26624
	ds_read_b128 v[244:247], v77 offset:26624
	v_mfma_f32_16x16x32_bf16 v[48:51], v[12:15], v[252:255], 0
	v_mfma_f32_16x16x32_bf16 v[64:67], v[92:95], v[158:161], v[64:67]
	v_mfma_f32_16x16x32_bf16 v[48:51], v[92:95], v[218:221], v[48:51]
	s_waitcnt lgkmcnt(4)
	v_mfma_f32_16x16x32_bf16 v[32:35], v[12:15], v[222:225], 0
	ds_read_b128 v[248:251], v75 offset:28672
	ds_read_b128 v[252:255], v75 offset:30720
	ds_read_b128 v[158:161], v77 offset:28672
	v_mfma_f32_16x16x32_bf16 v[16:19], v[12:15], v[96:99], 0
	v_mfma_f32_16x16x32_bf16 v[32:35], v[92:95], v[226:229], v[32:35]
	v_mfma_f32_16x16x32_bf16 v[16:19], v[92:95], v[154:157], v[16:19]
	s_waitcnt lgkmcnt(3)
	v_mfma_f32_16x16x32_bf16 v[60:63], v[12:15], v[232:235], 0
	v_mfma_f32_16x16x32_bf16 v[44:47], v[12:15], v[240:243], 0
	v_mfma_f32_16x16x32_bf16 v[60:63], v[92:95], v[236:239], v[60:63]
	v_mfma_f32_16x16x32_bf16 v[44:47], v[92:95], v[244:247], v[44:47]
	s_waitcnt lgkmcnt(1)
; template <bool PASS_C>
; DEVI void lru_item(const P& p, int item, int next_item, uint4& u0, uint4& u1, uint4& u2, float& cpre, char* smem) {
;     ...
;     float av[4][2][4], bv[4][2][4], apre[4][2], bpre[4][2];
; #pragma unroll
;     for (int nn = 0; nn < 4; ++nn) {
;         const int ch = 16 * nn + fr;
;         float uc[4];
; #pragma unroll
;         for (int j = 0; j < 4; ++j) {
;             const int tl = 16 * w + 4 * fq + j;
;             uc[j] = bf2f(*(const bf16_t*)(ucb + tl * 128 + ((((ch >> 3)) ^ (tl & 7)) << 4) + (ch & 7) * 2));
;         }
; #pragma unroll
;         for (int d = 0; d < 2; ++d) {
;             const float ba = prm[(5 + d) * 64 + ch], bx = prm[(7 + d) * 64 + ch], nsp8 = prm[(9 + d) * 64 + ch];
; #pragma unroll
;             for (int j = 0; j < 4; ++j) {
;                 const float r = __builtin_amdgcn_rcpf(1.0f + __builtin_amdgcn_exp2f(__builtin_fmaf(acc[(2 * d) * 4 + nn][j], -LOG2E, ba)));
;                 const float ig = __builtin_amdgcn_rcpf(1.0f + __builtin_amdgcn_exp2f(__builtin_fmaf(acc[(2 * d + 1) * 4 + nn][j], -LOG2E, bx)));
;                 const float a_ = __builtin_amdgcn_exp2f(nsp8 * r);
;                 av[nn][d][j] = a_;
;                 bv[nn][d][j] = __builtin_amdgcn_sqrtf(__builtin_fmaf(-a_, a_, 1.0f)) * ig * uc[j];
;             }
;             float A = 1.f, Bq = 0.f;
;             if (d == 0) {
; #pragma unroll
;                 for (int j = 0; j < 4; ++j) { Bq = av[nn][d][j] * Bq + bv[nn][d][j]; A *= av[nn][d][j]; }
;             } else {
; #pragma unroll
;                 for (int j = 3; j >= 0; --j) { Bq = av[nn][d][j] * Bq + bv[nn][d][j]; A *= av[nn][d][j]; }
;             }
;             float Ag[4], Bg[4];
;             rowgather4(A, Ag); rowgather4(Bq, Bg);
;             float AW = 1.f, BW = 0.f, AP = 1.f, BP = 0.f;
;             if (d == 0) {
; #pragma unroll
;                 for (int g = 0; g < 4; ++g) {
;                     if (g == fq) { AP = AW; BP = BW; }
;                     BW = Ag[g] * BW + Bg[g]; AW *= Ag[g];
;                 }
;             } else {
; #pragma unroll
;                 for (int g = 3; g >= 0; --g) {
;                     if (g == fq) { AP = AW; BP = BW; }
;                     BW = Ag[g] * BW + Bg[g]; AW *= Ag[g];
;                 }
;             }
;             apre[nn][d] = AP; bpre[nn][d] = BP;
	v_mfma_f32_16x16x32_bf16 v[28:31], v[12:15], v[248:251], 0
	v_mfma_f32_16x16x32_bf16 v[12:15], v[12:15], v[252:255], 0
	ds_read_b128 v[96:99], v77 offset:30720
	ds_read2st64_b32 v[154:155], v116 offset0:133 offset1:135
	ds_read_u16 v246, v121 offset:44544
	ds_read_u16 v247, v122 offset:44544
	ds_read_u16 v248, v123 offset:44544
	ds_read_u16 v249, v124 offset:44544
	ds_read2st64_b32 v[232:233], v116 offset0:134 offset1:136
	ds_read_b32 v250, v116 offset:35328
	v_add_u32_e32 v217, 64, v116
	ds_read2st64_b32 v[234:235], v217 offset0:133 offset1:135
	ds_read_u16 v251, v125 offset:44544
	ds_read_u16 v252, v126 offset:44544
	ds_read_u16 v253, v127 offset:44544
	ds_read_u16 v254, v128 offset:44544
	ds_read_b32 v255, v116 offset:35136
	v_add_u32_e32 v217, 64, v116
	ds_read2st64_b32 v[236:237], v217 offset0:134 offset1:136
	ds_read_b32 v218, v116 offset:35392
	v_add_u32_e32 v217, 0x80, v116
	ds_read2st64_b32 v[238:239], v217 offset0:133 offset1:135
	ds_read_u16 v219, v129 offset:44544
	ds_read_u16 v220, v130 offset:44544
	ds_read_u16 v221, v131 offset:44544
	ds_read_u16 v222, v132 offset:44544
	ds_read_b32 v223, v116 offset:35200
	v_add_u32_e32 v217, 0x80, v116
	ds_read2st64_b32 v[240:241], v217 offset0:134 offset1:136
	ds_read_b32 v224, v116 offset:35456
	v_add_u32_e32 v217, 0xc0, v116
	ds_read2st64_b32 v[242:243], v217 offset0:133 offset1:135
	ds_read_u16 v225, v133 offset:44544
	ds_read_u16 v226, v134 offset:44544
	ds_read_u16 v227, v135 offset:44544
	ds_read_u16 v228, v136 offset:44544
	ds_read_b32 v229, v116 offset:35264
	v_add_u32_e32 v217, 0xc0, v116
	ds_read2st64_b32 v[244:245], v217 offset0:134 offset1:136
	ds_read_b32 v231, v116 offset:35520
	s_waitcnt lgkmcnt(0)
	v_fmamk_f32 v81, v146, 0xbfb8aa3b, v154
	v_exp_f32_e32 v81, v81
	v_fmamk_f32 v91, v149, 0xbfb8aa3b, v154
	v_exp_f32_e32 v91, v91
	v_mfma_f32_16x16x32_bf16 v[28:31], v[92:95], v[158:161], v[28:31]
	v_add_f32_e32 v81, 1.0, v81
	v_rcp_f32_e32 v87, v81
	v_fmamk_f32 v81, v147, 0xbfb8aa3b, v154
	v_exp_f32_e32 v89, v81
	v_lshlrev_b32_e32 v81, 16, v249
	v_mul_f32_e32 v85, v83, v87
	v_mfma_f32_16x16x32_bf16 v[12:15], v[92:95], v[96:99], v[12:15]
	v_add_f32_e32 v87, 1.0, v89
	v_fmamk_f32 v89, v148, 0xbfb8aa3b, v154
	v_exp_f32_e32 v89, v89
	v_add_f32_e32 v91, 1.0, v91
	v_fmamk_f32 v93, v150, 0xbfb8aa3b, v155
	v_rcp_f32_e32 v87, v87
	v_add_f32_e32 v89, 1.0, v89
	v_exp_f32_e32 v85, v85
	v_rcp_f32_e32 v89, v89
	v_rcp_f32_e32 v91, v91
	v_exp_f32_e32 v93, v93
	v_mul_f32_e32 v87, v83, v87
	v_mul_f32_e32 v89, v83, v89
	v_mul_f32_e32 v83, v83, v91
	v_add_f32_e32 v91, 1.0, v93
	v_fma_f32 v93, -v85, v85, 1.0
	v_rcp_f32_e32 v91, v91
	v_sqrt_f32_e32 v93, v93
	v_fmamk_f32 v94, v151, 0xbfb8aa3b, v155
	v_exp_f32_e32 v87, v87
	v_exp_f32_e32 v94, v94
	v_lshlrev_b32_e32 v75, 16, v246
	v_mul_f32_e32 v91, v91, v93
	v_mul_f32_e32 v91, v91, v75
	v_mul_f32_e32 v92, v85, v87
	v_fmac_f32_e32 v91, 0, v85
	v_add_f32_e32 v85, 1.0, v94
	v_fma_f32 v93, -v87, v87, 1.0
	v_rcp_f32_e32 v85, v85
	v_sqrt_f32_e32 v93, v93
	v_mul_f32_e32 v87, v87, v91
	v_fmamk_f32 v91, v152, 0xbfb8aa3b, v155
	v_exp_f32_e32 v89, v89
	v_exp_f32_e32 v91, v91
	v_lshlrev_b32_e32 v77, 16, v247
	v_mul_f32_e32 v85, v85, v93
	v_fmac_f32_e32 v87, v85, v77
	v_fmamk_f32 v155, v153, 0xbfb8aa3b, v155
	v_exp_f32_e32 v83, v83
	v_mul_f32_e32 v85, v89, v87
	v_add_f32_e32 v87, 1.0, v91
	v_exp_f32_e32 v91, v155
	v_mul_f32_e32 v92, v89, v92
	v_fma_f32 v89, -v89, v89, 1.0
	v_rcp_f32_e32 v87, v87
	v_sqrt_f32_e32 v89, v89
	v_add_f32_e32 v91, 1.0, v91
	v_fma_f32 v93, -v83, v83, 1.0
	v_rcp_f32_e32 v91, v91
	v_sqrt_f32_e32 v93, v93
	v_lshlrev_b32_e32 v79, 16, v248
	v_mul_f32_e32 v87, v87, v89
	v_fmac_f32_e32 v85, v87, v79
	v_mul_f32_e32 v92, v83, v92
	v_mul_f32_e32 v83, v83, v85
	v_mul_f32_e32 v85, v91, v93
	v_fmac_f32_e32 v83, v85, v81
	v_mov_b32_e32 v96, v92
	v_mov_b32_e32 v85, v83
	s_nop 0
	v_permlane16_swap_b32_e32 v92, v96
	v_permlane16_swap_b32_e32 v83, v85
	v_mov_b32_e32 v94, v92
	v_mov_b32_e32 v95, v96
	v_mov_b32_e32 v97, v83
	v_mov_b32_e32 v99, v85
	v_permlane32_swap_b32_e32 v92, v94
	v_permlane32_swap_b32_e32 v96, v95
	v_permlane32_swap_b32_e32 v83, v97
	v_permlane32_swap_b32_e32 v85, v99
	s_and_saveexec_b64 s[12:13], s[8:9]
	s_cbranch_execz .LBB0_512
	v_fmac_f32_e32 v83, 0, v92
	v_fmac_f32_e32 v85, v83, v96
	v_mul_f32_e32 v93, v85, v94
	v_pk_mul_f32 v[146:147], v[92:93], v[96:97]
	v_pk_add_f32 v[92:93], v[92:93], v[96:97]
	v_mov_b32_e32 v96, v95
	v_mov_b32_e32 v92, v146
	v_mov_b32_e32 v98, v95
	v_pk_mul_f32 v[146:147], v[146:147], v[94:95]
	v_pk_fma_f32 v[92:93], v[92:93], v[94:95], v[98:99]
	v_pk_mul_f32 v[96:97], v[146:147], v[96:97]
	s_nop 0
	v_mov_b32_e32 v97, v93
	ds_write_b64 v141, v[96:97] offset:52736

; DEVI unsigned pk2(float lo, float hi) { f32x2 v = {lo, hi}; bf16x2_t b = __builtin_convertvector(v, bf16x2_t); return __builtin_bit_cast(unsigned, b); }
; DEVI float bflo(unsigned u) { return __uint_as_float(u << 16); }
; DEVI float bfhi(unsigned u) { return __uint_as_float(u & 0xffff0000u); }
; template <bool PASS_C>
; DEVI void lru_item(const P& p, int item, int next_item, uint4& u0, uint4& u1, uint4& u2, float& cpre, char* smem) {
;     ...
;     {
;         const int tok = tid >> 2, cg0 = (tid & 3) * 16;
;         uint4 r[4][2];
; #pragma unroll
;         for (int k = 0; k < 4; ++k) { r[k][0] = *(const uint4*)(us + (tok + k) * 64 + cg0); r[k][1] = *(const uint4*)(us + (tok + k) * 64 + cg0 + 8); }
;         float val[16];
; #pragma unroll
;         for (int e = 0; e < 16; ++e) {
;             const int ch = cg0 + e;
;             float a = prm[4 * 64 + ch];
; #pragma unroll
;             for (int k = 0; k < 4; ++k) {
;                 const uint4 q = r[k][e >> 3];
;                 const unsigned wd = ((e >> 1) & 3) == 0 ? q.x : (((e >> 1) & 3) == 1 ? q.y : (((e >> 1) & 3) == 2 ? q.z : q.w));
;                 a += prm[k * 64 + ch] * ((e & 1) ? bfhi(wd) : bflo(wd));
;             }
;             val[e] = a;
;         }
;         uint4 o;
;         o.x = pk2(val[0], val[1]); o.y = pk2(val[2], val[3]); o.z = pk2(val[4], val[5]); o.w = pk2(val[6], val[7]);
;         *(uint4*)(ucb + tok * 128 + ((((cg0 >> 3) + 0) ^ (tok & 7)) << 4)) = o;
;         o.x = pk2(val[8], val[9]); o.y = pk2(val[10], val[11]); o.z = pk2(val[12], val[13]); o.w = pk2(val[14], val[15]);
;         *(uint4*)(ucb + tok * 128 + ((((cg0 >> 3) + 1) ^ (tok & 7)) << 4)) = o;
;     }
.LBB0_739:
	v_lshlrev_b64 v[106:107], 10, v[22:23]
	s_waitcnt lgkmcnt(0)
	s_barrier
	ds_read_b128 v[42:45], v127 offset:35840
	ds_read_b128 v[22:25], v127 offset:35856
	ds_read_b128 v[46:49], v127 offset:35968
	ds_read_b128 v[26:29], v127 offset:35984
	ds_read_b128 v[50:53], v127 offset:36096
	ds_read_b128 v[30:33], v127 offset:36112
	ds_read_b128 v[54:57], v127 offset:36224
	ds_read_b128 v[34:37], v127 offset:36240
	ds_read_b128 v[58:61], v117 offset:33792
	ds_read_b128 v[62:65], v117 offset:32768
	ds_read_b128 v[66:69], v117 offset:32784
	ds_read_b128 v[70:73], v117 offset:32800
	ds_read_b128 v[38:41], v117 offset:32816
	ds_read_b128 v[74:77], v117 offset:33024
	ds_read_b128 v[158:161], v117 offset:33808
	s_waitcnt lgkmcnt(14)
	v_lshlrev_b32_e32 v162, 16, v42
	v_and_b32_e32 v163, 0xffff0000, v42
	s_waitcnt lgkmcnt(5)
	v_pk_fma_f32 v[58:59], v[62:63], v[162:163], v[58:59]
	ds_read_b128 v[162:165], v117 offset:33280
	ds_read_b128 v[166:169], v117 offset:33536
	ds_read_b128 v[184:187], v117 offset:33040
	v_lshlrev_b32_e32 v42, 16, v43
	v_and_b32_e32 v43, 0xffff0000, v43
	v_lshlrev_b32_e32 v170, 16, v46
	v_and_b32_e32 v171, 0xffff0000, v46
	v_lshlrev_b32_e32 v46, 16, v47
	v_and_b32_e32 v47, 0xffff0000, v47
	v_pk_fma_f32 v[42:43], v[64:65], v[42:43], v[60:61]
	v_lshlrev_b32_e32 v192, 16, v50
	v_and_b32_e32 v193, 0xffff0000, v50
	s_waitcnt lgkmcnt(4)
	v_pk_fma_f32 v[58:59], v[74:75], v[170:171], v[58:59]
	ds_read_b128 v[188:191], v117 offset:33296
	v_lshlrev_b32_e32 v50, 16, v51
	v_and_b32_e32 v51, 0xffff0000, v51
	v_pk_fma_f32 v[42:43], v[76:77], v[46:47], v[42:43]
	v_lshlrev_b32_e32 v196, 16, v54
	v_and_b32_e32 v197, 0xffff0000, v54
	s_waitcnt lgkmcnt(3)
	v_pk_fma_f32 v[58:59], v[162:163], v[192:193], v[58:59]
	ds_read_b128 v[192:195], v117 offset:33552
	v_lshlrev_b32_e32 v54, 16, v55
	v_and_b32_e32 v55, 0xffff0000, v55
	v_pk_fma_f32 v[42:43], v[164:165], v[50:51], v[42:43]
	v_lshlrev_b32_e32 v46, 16, v48
	s_waitcnt lgkmcnt(3)
	v_pk_fma_f32 v[164:165], v[168:169], v[54:55], v[42:43]
	v_lshlrev_b32_e32 v42, 16, v44
	v_and_b32_e32 v43, 0xffff0000, v44
	v_and_b32_e32 v47, 0xffff0000, v48
	v_pk_fma_f32 v[42:43], v[66:67], v[42:43], v[158:159]
	v_lshlrev_b32_e32 v50, 16, v52
	v_and_b32_e32 v51, 0xffff0000, v52
	s_waitcnt lgkmcnt(2)
	v_pk_fma_f32 v[42:43], v[184:185], v[46:47], v[42:43]
	v_lshlrev_b32_e32 v54, 16, v56
	v_and_b32_e32 v55, 0xffff0000, v56
	s_waitcnt lgkmcnt(1)
	v_pk_fma_f32 v[42:43], v[188:189], v[50:51], v[42:43]
	v_lshlrev_b32_e32 v44, 16, v49
	s_waitcnt lgkmcnt(0)
	v_pk_fma_f32 v[158:159], v[192:193], v[54:55], v[42:43]
	v_lshlrev_b32_e32 v42, 16, v45
	v_and_b32_e32 v43, 0xffff0000, v45
	v_and_b32_e32 v45, 0xffff0000, v49
	v_pk_fma_f32 v[42:43], v[68:69], v[42:43], v[160:161]
	v_lshlrev_b32_e32 v46, 16, v53
	v_and_b32_e32 v47, 0xffff0000, v53
	v_pk_fma_f32 v[42:43], v[186:187], v[44:45], v[42:43]
	v_lshlrev_b32_e32 v48, 16, v57
	v_and_b32_e32 v49, 0xffff0000, v57
	v_pk_fma_f32 v[42:43], v[190:191], v[46:47], v[42:43]
	v_lshlrev_b32_e32 v54, 16, v22
	v_pk_fma_f32 v[160:161], v[194:195], v[48:49], v[42:43]
	ds_read_b128 v[42:45], v117 offset:33824
	ds_read_b128 v[46:49], v117 offset:33056
	ds_read_b128 v[50:53], v117 offset:33840
	v_and_b32_e32 v55, 0xffff0000, v22
	v_pk_fma_f32 v[162:163], v[166:167], v[196:197], v[58:59]
	v_lshlrev_b32_e32 v22, 16, v23
	s_waitcnt lgkmcnt(2)
	v_pk_fma_f32 v[42:43], v[70:71], v[54:55], v[42:43]
	ds_read_b128 v[54:57], v117 offset:33312
	ds_read_b128 v[58:61], v117 offset:33568
	ds_read_b128 v[62:65], v117 offset:33072
	v_and_b32_e32 v23, 0xffff0000, v23
	v_lshlrev_b32_e32 v66, 16, v26
	v_and_b32_e32 v67, 0xffff0000, v26
	v_lshlrev_b32_e32 v26, 16, v27
	v_and_b32_e32 v27, 0xffff0000, v27
	v_pk_fma_f32 v[22:23], v[72:73], v[22:23], v[44:45]
	v_lshlrev_b32_e32 v74, 16, v30
	v_and_b32_e32 v75, 0xffff0000, v30
	s_waitcnt lgkmcnt(4)
	v_pk_fma_f32 v[42:43], v[46:47], v[66:67], v[42:43]
	ds_read_b128 v[66:69], v117 offset:33328
	v_lshlrev_b32_e32 v30, 16, v31
	v_and_b32_e32 v31, 0xffff0000, v31
	v_pk_fma_f32 v[22:23], v[48:49], v[26:27], v[22:23]
	v_lshlrev_b32_e32 v166, 16, v34
	v_and_b32_e32 v167, 0xffff0000, v34
	s_waitcnt lgkmcnt(3)
	v_pk_fma_f32 v[42:43], v[54:55], v[74:75], v[42:43]
	ds_read_b128 v[74:77], v117 offset:33584
	v_lshlrev_b32_e32 v34, 16, v35
	v_and_b32_e32 v35, 0xffff0000, v35
	v_pk_fma_f32 v[22:23], v[56:57], v[30:31], v[22:23]
	v_lshlrev_b32_e32 v30, 16, v28
	s_waitcnt lgkmcnt(3)
	v_pk_fma_f32 v[26:27], v[60:61], v[34:35], v[22:23]
	v_lshlrev_b32_e32 v22, 16, v24
	v_and_b32_e32 v23, 0xffff0000, v24
	v_and_b32_e32 v31, 0xffff0000, v28
	v_pk_fma_f32 v[22:23], v[38:39], v[22:23], v[50:51]
	v_lshlrev_b32_e32 v34, 16, v32
	v_and_b32_e32 v35, 0xffff0000, v32
	s_waitcnt lgkmcnt(2)
	v_pk_fma_f32 v[22:23], v[62:63], v[30:31], v[22:23]
	v_lshlrev_b32_e32 v44, 16, v36
	v_and_b32_e32 v45, 0xffff0000, v36
	s_waitcnt lgkmcnt(1)
	v_pk_fma_f32 v[22:23], v[66:67], v[34:35], v[22:23]
	v_lshlrev_b32_e32 v24, 16, v29
	s_waitcnt lgkmcnt(0)
	v_pk_fma_f32 v[30:31], v[74:75], v[44:45], v[22:23]
	v_lshlrev_b32_e32 v22, 16, v25
	v_and_b32_e32 v23, 0xffff0000, v25
	v_and_b32_e32 v25, 0xffff0000, v29
	v_pk_fma_f32 v[22:23], v[40:41], v[22:23], v[52:53]
	v_lshlrev_b32_e32 v28, 16, v33
	v_and_b32_e32 v29, 0xffff0000, v33
	v_pk_fma_f32 v[22:23], v[64:65], v[24:25], v[22:23]
	v_lshlrev_b32_e32 v32, 16, v37
	v_and_b32_e32 v33, 0xffff0000, v37
	v_pk_fma_f32 v[22:23], v[68:69], v[28:29], v[22:23]
	v_pk_fma_f32 v[42:43], v[58:59], v[166:167], v[42:43]
	v_pk_fma_f32 v[28:29], v[76:77], v[32:33], v[22:23]
	v_cvt_pk_bf16_f32 v22, v162, v163
	v_cvt_pk_bf16_f32 v23, v164, v165
	v_cvt_pk_bf16_f32 v24, v158, v159
	v_cvt_pk_bf16_f32 v25, v160, v161
	ds_write_b128 v128, v[22:25] offset:44544
	v_cvt_pk_bf16_f32 v22, v42, v43
	v_cvt_pk_bf16_f32 v23, v26, v27
	v_cvt_pk_bf16_f32 v24, v30, v31
	v_cvt_pk_bf16_f32 v25, v28, v29
	ds_write_b128 v129, v[22:25] offset:44544
	v_add_u32_e32 v22, v119, v120
	s_waitcnt lgkmcnt(0)
; DEVI float bf2f(bf16_t h) { return __uint_as_float(((unsigned)h) << 16); }
; template <bool PASS_C>
; DEVI void lru_item(const P& p, int item, int next_item, uint4& u0, uint4& u1, uint4& u2, float& cpre, char* smem) {
;     ...
;     f32x4 acc[16];
; #pragma unroll
;     for (int n = 0; n < 16; ++n) acc[n] = (f32x4){0.f, 0.f, 0.f, 0.f};
;     {
;         bf16x8 af[2];
; #pragma unroll
;         for (int kk = 0; kk < 2; ++kk) af[kk] = *(const bf16x8*)(ucb + (16 * w + fr) * 128 + (((kk * 4 + fq) ^ (fr & 7)) << 4));
; #pragma unroll
;         for (int n = 0; n < 16; ++n)
; #pragma unroll
;             for (int kk = 0; kk < 2; ++kk) {
;                 const bf16x8 bfr = *(const bf16x8*)(smem + (16 * n + fr) * 128 + (((kk * 4 + fq) ^ (fr & 7)) << 4));
;                 acc[n] = __builtin_amdgcn_mfma_f32_16x16x32_bf16(af[kk], bfr, acc[n], 0, 0, 0);
;             }
;     }
;     float av[4][2][4], bv[4][2][4], apre[4][2], bpre[4][2];
; #pragma unroll
;     for (int nn = 0; nn < 4; ++nn) {
;         const int ch = 16 * nn + fr;
;         float uc[4];
; #pragma unroll
;         for (int j = 0; j < 4; ++j) {
;             const int tl = 16 * w + 4 * fq + j;
;             uc[j] = bf2f(*(const bf16_t*)(ucb + tl * 128 + ((((ch >> 3)) ^ (tl & 7)) << 4) + (ch & 7) * 2));
;         }
; #pragma unroll
;         for (int d = 0; d < 2; ++d) {
;             const float ba = prm[(5 + d) * 64 + ch], bx = prm[(7 + d) * 64 + ch], nsp8 = prm[(9 + d) * 64 + ch];
	v_add_u32_e32 v87, v118, v120
	v_add_u32_e32 v30, v119, v121
	v_add_u32_e32 v89, v118, v121
	ds_read_b128 v[26:29], v22 offset:44544
	ds_read_b128 v[158:161], v30 offset:44544
	ds_read_b32 v93, v122 offset:35072
	ds_read_b128 v[232:235], v87
	ds_read_b128 v[236:239], v89
	ds_read_b128 v[240:243], v87 offset:2048
	ds_read_b128 v[244:247], v89 offset:2048
	ds_read_b128 v[248:251], v87 offset:4096
	ds_read_b128 v[192:195], v89 offset:4096
	ds_read_b128 v[252:255], v87 offset:6144
	ds_read_b128 v[218:221], v89 offset:6144
	s_waitcnt lgkmcnt(4)
	v_mfma_f32_16x16x32_bf16 v[166:169], v[26:29], v[232:235], 0
	ds_read_b128 v[222:225], v87 offset:8192
	ds_read_b128 v[226:229], v89 offset:8192
	ds_read_b128 v[162:165], v87 offset:10240
	ds_read_b128 v[188:191], v89 offset:10240
	v_mfma_f32_16x16x32_bf16 v[62:65], v[26:29], v[240:243], 0
	v_mfma_f32_16x16x32_bf16 v[166:169], v[158:161], v[236:239], v[166:169]
	v_mfma_f32_16x16x32_bf16 v[62:65], v[158:161], v[244:247], v[62:65]
	s_waitcnt lgkmcnt(4)
	v_mfma_f32_16x16x32_bf16 v[46:49], v[26:29], v[248:251], 0
	ds_read_b128 v[232:235], v87 offset:12288
	ds_read_b128 v[236:239], v89 offset:12288
	ds_read_b128 v[240:243], v87 offset:14336
	ds_read_b128 v[244:247], v89 offset:14336
	v_mfma_f32_16x16x32_bf16 v[30:33], v[26:29], v[252:255], 0
	v_mfma_f32_16x16x32_bf16 v[46:49], v[158:161], v[192:195], v[46:49]
	v_mfma_f32_16x16x32_bf16 v[30:33], v[158:161], v[218:221], v[30:33]
	s_waitcnt lgkmcnt(4)
	v_mfma_f32_16x16x32_bf16 v[184:187], v[26:29], v[222:225], 0
	ds_read_b128 v[248:251], v87 offset:16384
	ds_read_b128 v[192:195], v89 offset:16384
	ds_read_b128 v[252:255], v87 offset:18432
	ds_read_b128 v[218:221], v89 offset:18432
	v_mfma_f32_16x16x32_bf16 v[66:69], v[26:29], v[162:165], 0
	v_mfma_f32_16x16x32_bf16 v[184:187], v[158:161], v[226:229], v[184:187]
	v_mfma_f32_16x16x32_bf16 v[66:69], v[158:161], v[188:191], v[66:69]
	s_waitcnt lgkmcnt(4)
	v_mfma_f32_16x16x32_bf16 v[50:53], v[26:29], v[232:235], 0
	ds_read_b128 v[222:225], v87 offset:20480
	ds_read_b128 v[226:229], v89 offset:20480
	ds_read_b128 v[162:165], v87 offset:22528
	ds_read_b128 v[188:191], v89 offset:22528
	v_mfma_f32_16x16x32_bf16 v[34:37], v[26:29], v[240:243], 0
	v_mfma_f32_16x16x32_bf16 v[50:53], v[158:161], v[236:239], v[50:53]
	v_mfma_f32_16x16x32_bf16 v[34:37], v[158:161], v[244:247], v[34:37]
	s_waitcnt lgkmcnt(4)
	v_mfma_f32_16x16x32_bf16 v[70:73], v[26:29], v[248:251], 0
	ds_read_b128 v[232:235], v87 offset:24576
	ds_read_b128 v[236:239], v89 offset:24576
	ds_read_b128 v[240:243], v87 offset:26624
	ds_read_b128 v[244:247], v89 offset:26624
	v_mfma_f32_16x16x32_bf16 v[54:57], v[26:29], v[252:255], 0
	v_mfma_f32_16x16x32_bf16 v[70:73], v[158:161], v[192:195], v[70:73]
	v_mfma_f32_16x16x32_bf16 v[54:57], v[158:161], v[218:221], v[54:57]
	s_waitcnt lgkmcnt(4)
	v_mfma_f32_16x16x32_bf16 v[38:41], v[26:29], v[222:225], 0
	ds_read_b128 v[248:251], v87 offset:28672
	ds_read_b128 v[252:255], v87 offset:30720
	ds_read_b128 v[192:195], v89 offset:28672
	v_mfma_f32_16x16x32_bf16 v[22:25], v[26:29], v[162:165], 0
	v_mfma_f32_16x16x32_bf16 v[38:41], v[158:161], v[226:229], v[38:41]
	v_mfma_f32_16x16x32_bf16 v[22:25], v[158:161], v[188:191], v[22:25]
	s_waitcnt lgkmcnt(3)
	v_mfma_f32_16x16x32_bf16 v[74:77], v[26:29], v[232:235], 0
	v_mfma_f32_16x16x32_bf16 v[58:61], v[26:29], v[240:243], 0
	v_mfma_f32_16x16x32_bf16 v[74:77], v[158:161], v[236:239], v[74:77]
	v_mfma_f32_16x16x32_bf16 v[58:61], v[158:161], v[244:247], v[58:61]
	s_waitcnt lgkmcnt(1)
	v_mfma_f32_16x16x32_bf16 v[42:45], v[26:29], v[248:251], 0
	v_mfma_f32_16x16x32_bf16 v[26:29], v[26:29], v[252:255], 0
	ds_read_b128 v[162:165], v89 offset:30720
	ds_read2st64_b32 v[170:171], v122 offset0:133 offset1:135
	ds_read_u16 v246, v130 offset:44544
	ds_read_u16 v247, v131 offset:44544
	ds_read_u16 v248, v132 offset:44544
	ds_read_u16 v249, v133 offset:44544
	ds_read2st64_b32 v[232:233], v122 offset0:134 offset1:136
	ds_read_b32 v250, v122 offset:35328
	v_add_u32_e32 v217, 64, v122
	ds_read2st64_b32 v[234:235], v217 offset0:133 offset1:135
	ds_read_u16 v251, v134 offset:44544
	ds_read_u16 v252, v135 offset:44544
	ds_read_u16 v253, v136 offset:44544
	ds_read_u16 v254, v137 offset:44544
	ds_read_b32 v255, v122 offset:35136
	v_add_u32_e32 v217, 64, v122
	ds_read2st64_b32 v[236:237], v217 offset0:134 offset1:136
	ds_read_b32 v218, v122 offset:35392
	v_add_u32_e32 v217, 0x80, v122
	ds_read2st64_b32 v[238:239], v217 offset0:133 offset1:135
	ds_read_u16 v219, v138 offset:44544
	ds_read_u16 v220, v139 offset:44544
	ds_read_u16 v221, v140 offset:44544
	ds_read_u16 v222, v141 offset:44544
	ds_read_b32 v223, v122 offset:35200
	v_add_u32_e32 v217, 0x80, v122
	ds_read2st64_b32 v[240:241], v217 offset0:134 offset1:136
	ds_read_b32 v224, v122 offset:35456
	v_add_u32_e32 v217, 0xc0, v122
	ds_read2st64_b32 v[242:243], v217 offset0:133 offset1:135
	ds_read_u16 v225, v142 offset:44544
	ds_read_u16 v226, v143 offset:44544
	ds_read_u16 v227, v144 offset:44544
	ds_read_u16 v228, v145 offset:44544
	ds_read_b32 v229, v122 offset:35264
	v_add_u32_e32 v217, 0xc0, v122
	ds_read2st64_b32 v[244:245], v217 offset0:134 offset1:136
	ds_read_b32 v231, v122 offset:35520
	s_waitcnt lgkmcnt(0)
; template <bool PASS_C>
; DEVI void lru_item(const P& p, int item, int next_item, uint4& u0, uint4& u1, uint4& u2, float& cpre, char* smem) {
;     ...
;         for (int d = 0; d < 2; ++d) {
;             const float ba = prm[(5 + d) * 64 + ch], bx = prm[(7 + d) * 64 + ch], nsp8 = prm[(9 + d) * 64 + ch];
; #pragma unroll
;             for (int j = 0; j < 4; ++j) {
;                 const float r = __builtin_amdgcn_rcpf(1.0f + __builtin_amdgcn_exp2f(__builtin_fmaf(acc[(2 * d) * 4 + nn][j], -LOG2E, ba)));
;                 const float ig = __builtin_amdgcn_rcpf(1.0f + __builtin_amdgcn_exp2f(__builtin_fmaf(acc[(2 * d + 1) * 4 + nn][j], -LOG2E, bx)));
;                 const float a_ = __builtin_amdgcn_exp2f(nsp8 * r);
;                 av[nn][d][j] = a_;
;                 bv[nn][d][j] = __builtin_amdgcn_sqrtf(__builtin_fmaf(-a_, a_, 1.0f)) * ig * uc[j];
;             }
;             float A = 1.f, Bq = 0.f;
;             if (d == 0) {
; #pragma unroll
;                 for (int j = 0; j < 4; ++j) { Bq = av[nn][d][j] * Bq + bv[nn][d][j]; A *= av[nn][d][j]; }
;             } else {
; #pragma unroll
;                 for (int j = 3; j >= 0; --j) { Bq = av[nn][d][j] * Bq + bv[nn][d][j]; A *= av[nn][d][j]; }
;             }
;             float Ag[4], Bg[4];
;             rowgather4(A, Ag); rowgather4(Bq, Bg);
;             float AW = 1.f, BW = 0.f, AP = 1.f, BP = 0.f;
;             if (d == 0) {
; #pragma unroll
;                 for (int g = 0; g < 4; ++g) {
;                     if (g == fq) { AP = AW; BP = BW; }
;                     BW = Ag[g] * BW + Bg[g]; AW *= Ag[g];
;                 }
;             } else {
; #pragma unroll
;                 for (int g = 3; g >= 0; --g) {
;                     if (g == fq) { AP = AW; BP = BW; }
;                     BW = Ag[g] * BW + Bg[g]; AW *= Ag[g];
;                 }
;             }
;             apre[nn][d] = AP; bpre[nn][d] = BP;
;             if (fq == 0) { wagg[((w * 2 + d) * 64 + ch) * 2 + 0] = AW; wagg[((w * 2 + d) * 64 + ch) * 2 + 1] = BW; }
	v_fmamk_f32 v95, v166, 0xbfb8aa3b, v170
	v_exp_f32_e32 v95, v95
	v_mfma_f32_16x16x32_bf16 v[42:45], v[158:161], v[192:195], v[42:45]
	v_fmamk_f32 v99, v168, 0xbfb8aa3b, v170
	v_fmamk_f32 v101, v186, 0xbfb8aa3b, v171
	v_exp_f32_e32 v99, v99
	v_mfma_f32_16x16x32_bf16 v[26:29], v[158:161], v[162:165], v[26:29]
	v_lshlrev_b32_e32 v164, 16, v246
	v_lshlrev_b32_e32 v161, 16, v247
	v_add_f32_e32 v87, 1.0, v95
	v_fmamk_f32 v89, v184, 0xbfb8aa3b, v171
	v_exp_f32_e32 v89, v89
	v_rcp_f32_e32 v87, v87
	v_lshlrev_b32_e32 v162, 16, v248
	v_add_f32_e32 v95, 1.0, v89
	v_mul_f32_e32 v87, v93, v87
	v_exp_f32_e32 v89, v87
	v_rcp_f32_e32 v87, v95
	v_fmamk_f32 v95, v167, 0xbfb8aa3b, v170
	v_exp_f32_e32 v95, v95
	v_lshlrev_b32_e32 v163, 16, v249
	v_fma_f32 v97, -v89, v89, 1.0
	v_sqrt_f32_e32 v97, v97
	v_add_f32_e32 v91, 1.0, v95
	v_rcp_f32_e32 v91, v91
	v_fmamk_f32 v95, v185, 0xbfb8aa3b, v171
	v_exp_f32_e32 v95, v95
	v_mul_f32_e32 v87, v87, v97
	v_mul_f32_e32 v91, v93, v91
	v_exp_f32_e32 v91, v91
	v_add_f32_e32 v95, 1.0, v95
	v_rcp_f32_e32 v95, v95
	v_exp_f32_e32 v101, v101
	v_fma_f32 v97, -v91, v91, 1.0
	v_sqrt_f32_e32 v97, v97
	v_fmamk_f32 v171, v187, 0xbfb8aa3b, v171
	v_exp_f32_e32 v105, v171
	v_mul_f32_e32 v87, v87, v164
	v_mul_f32_e32 v97, v95, v97
	v_add_f32_e32 v95, 1.0, v99
	v_add_f32_e32 v99, 1.0, v101
	v_fmamk_f32 v101, v169, 0xbfb8aa3b, v170
	v_exp_f32_e32 v101, v101
	v_rcp_f32_e32 v95, v95
	v_rcp_f32_e32 v99, v99
	v_add_f32_e32 v101, 1.0, v101
	v_rcp_f32_e32 v101, v101
	v_mul_f32_e32 v95, v93, v95
	v_exp_f32_e32 v95, v95
	v_mul_f32_e32 v93, v93, v101
	v_exp_f32_e32 v101, v93
	v_add_f32_e32 v93, 1.0, v105
	v_fma_f32 v103, -v95, v95, 1.0
	v_rcp_f32_e32 v105, v93
	v_fma_f32 v93, -v101, v101, 1.0
	v_sqrt_f32_e32 v103, v103
	v_sqrt_f32_e32 v157, v93
	v_mul_f32_e32 v93, v97, v161
	v_mul_f32_e32 v97, v99, v103
	v_mul_f32_e32 v99, v105, v157
	v_fma_f32 v105, 0, v89, v87
	v_mul_f32_e32 v97, v97, v162
	v_mul_f32_e32 v103, v89, v91
	v_fma_f32 v105, v91, v105, v93
	v_mul_f32_e32 v99, v99, v163
	v_mul_f32_e32 v103, v95, v103
	v_fma_f32 v105, v95, v105, v97
	v_mul_f32_e32 v103, v101, v103
	v_fma_f32 v105, v101, v105, v99
	v_mov_b32_e32 v159, v103
	v_mov_b32_e32 v157, v105
	s_nop 0
	v_permlane16_swap_b32_e32 v103, v159
	v_permlane16_swap_b32_e32 v105, v157
	v_mov_b32_e32 v160, v103
	v_mov_b32_e32 v158, v105
	s_nop 0
	v_permlane32_swap_b32_e32 v103, v160
	v_mov_b32_e32 v165, v159
	v_permlane32_swap_b32_e32 v105, v158
	v_mov_b32_e32 v166, v157
	v_permlane32_swap_b32_e32 v159, v165
	s_nop 0
	v_permlane32_swap_b32_e32 v157, v166
	v_fmac_f32_e32 v105, 0, v103
	v_fmac_f32_e32 v157, v105, v159
	v_mul_f32_e32 v159, v103, v159
	v_fmac_f32_e32 v158, v157, v160
	v_mul_f32_e32 v160, v159, v160
	s_and_saveexec_b64 s[28:29], s[10:11]
	v_mul_f32_e32 v167, v158, v165
	v_mul_f32_e32 v168, v160, v165
	v_add_f32_e32 v169, v167, v166
	ds_write_b64 v149, v[168:169] offset:52736
	s_or_b64 exec, exec, s[28:29]
	v_fmamk_f32 v70, v70, 0xbfb8aa3b, v232
	v_exp_f32_e32 v70, v70
	v_fmamk_f32 v71, v71, 0xbfb8aa3b, v232
	v_exp_f32_e32 v71, v71
	v_fmamk_f32 v74, v74, 0xbfb8aa3b, v233
	v_add_f32_e32 v70, 1.0, v70
	v_rcp_f32_e32 v70, v70
	v_add_f32_e32 v71, 1.0, v71
	v_exp_f32_e32 v74, v74
	v_rcp_f32_e32 v71, v71
	v_mul_f32_e32 v70, v250, v70
	v_exp_f32_e32 v70, v70
	v_fmamk_f32 v75, v75, 0xbfb8aa3b, v233
	v_add_f32_e32 v74, 1.0, v74
	v_mul_f32_e32 v71, v250, v71
	v_fma_f32 v168, -v70, v70, 1.0
	v_fmamk_f32 v72, v72, 0xbfb8aa3b, v232
	v_fmamk_f32 v73, v73, 0xbfb8aa3b, v232
	v_exp_f32_e32 v75, v75
	v_rcp_f32_e32 v74, v74
	v_exp_f32_e32 v71, v71
	v_sqrt_f32_e32 v168, v168
	v_exp_f32_e32 v72, v72
	v_exp_f32_e32 v73, v73
	v_add_f32_e32 v75, 1.0, v75
	v_fma_f32 v169, -v71, v71, 1.0
	v_mul_f32_e32 v74, v74, v168
	v_fmamk_f32 v76, v76, 0xbfb8aa3b, v233
	v_add_f32_e32 v72, 1.0, v72
	v_add_f32_e32 v73, 1.0, v73
	v_rcp_f32_e32 v75, v75
	v_mul_f32_e32 v74, v74, v164
	v_sqrt_f32_e32 v164, v169
	v_exp_f32_e32 v76, v76
	v_rcp_f32_e32 v72, v72
	v_rcp_f32_e32 v73, v73
	v_fmamk_f32 v167, v77, 0xbfb8aa3b, v233
	v_mul_f32_e32 v164, v75, v164
	v_add_f32_e32 v75, 1.0, v76
	v_mul_f32_e32 v72, v250, v72
	v_exp_f32_e32 v77, v167
	v_mul_f32_e32 v73, v250, v73
	v_exp_f32_e32 v72, v72
	v_rcp_f32_e32 v76, v75
	v_exp_f32_e32 v75, v73
	v_add_f32_e32 v73, 1.0, v77
	v_fma_f32 v166, -v72, v72, 1.0
	v_rcp_f32_e32 v77, v73
	v_fma_f32 v73, -v75, v75, 1.0
	v_sqrt_f32_e32 v165, v166
	v_sqrt_f32_e32 v166, v73
	v_mul_f32_e32 v73, v164, v161
	v_mul_f32_e32 v161, v75, v72
	v_mul_f32_e32 v76, v76, v165
	v_mul_f32_e32 v77, v77, v166
	v_mul_f32_e32 v77, v77, v163
	v_mul_f32_e32 v161, v71, v161
	v_mul_f32_e32 v76, v76, v162
	v_mul_f32_e32 v165, v70, v161
	v_fma_f32 v161, 0, v75, v77
	v_fma_f32 v161, v72, v161, v76
	v_fma_f32 v161, v71, v161, v73
	v_fma_f32 v168, v70, v161, v74
	v_mov_b32_e32 v167, v165
	v_mov_b32_e32 v161, v168
	s_nop 0
	v_permlane16_swap_b32_e32 v165, v167
	v_permlane16_swap_b32_e32 v168, v161
	v_mov_b32_e32 v162, v167
	v_mov_b32_e32 v164, v161
	v_mov_b32_e32 v166, v165
	v_permlane32_swap_b32_e32 v167, v162
	v_mov_b32_e32 v163, v168
	v_permlane32_swap_b32_e32 v161, v164
	v_permlane32_swap_b32_e32 v165, v166
	v_permlane32_swap_b32_e32 v168, v163
	v_fmac_f32_e32 v164, 0, v162
	v_fmac_f32_e32 v163, v164, v166
	v_mul_f32_e32 v166, v166, v162
	v_fmac_f32_e32 v161, v163, v167
	v_mul_f32_e32 v167, v166, v167
	s_and_saveexec_b64 s[28:29], s[10:11]
	v_mul_f32_e32 v169, v161, v165
	v_mul_f32_e32 v170, v167, v165
	v_add_f32_e32 v171, v169, v168
	ds_write_b64 v149, v[170:171] offset:53248
	s_or_b64 exec, exec, s[28:29]
	v_lshlrev_b32_e32 v185, 16, v251
	v_lshlrev_b32_e32 v183, 16, v252
	v_lshlrev_b32_e32 v177, 16, v253
; template <bool PASS_C>
; DEVI void lru_item(const P& p, int item, int next_item, uint4& u0, uint4& u1, uint4& u2, float& cpre, char* smem) {
;     ...
;         for (int d = 0; d < 2; ++d) {
;             const float ba = prm[(5 + d) * 64 + ch], bx = prm[(7 + d) * 64 + ch], nsp8 = prm[(9 + d) * 64 + ch];
; #pragma unroll
;             for (int j = 0; j < 4; ++j) {
;                 const float r = __builtin_amdgcn_rcpf(1.0f + __builtin_amdgcn_exp2f(__builtin_fmaf(acc[(2 * d) * 4 + nn][j], -LOG2E, ba)));
;                 const float ig = __builtin_amdgcn_rcpf(1.0f + __builtin_amdgcn_exp2f(__builtin_fmaf(acc[(2 * d + 1) * 4 + nn][j], -LOG2E, bx)));
;                 const float a_ = __builtin_amdgcn_exp2f(nsp8 * r);
;                 av[nn][d][j] = a_;
;                 bv[nn][d][j] = __builtin_amdgcn_sqrtf(__builtin_fmaf(-a_, a_, 1.0f)) * ig * uc[j];
;             }
;             float A = 1.f, Bq = 0.f;
;             if (d == 0) {
; #pragma unroll
;                 for (int j = 0; j < 4; ++j) { Bq = av[nn][d][j] * Bq + bv[nn][d][j]; A *= av[nn][d][j]; }
;             } else {
; #pragma unroll
;                 for (int j = 3; j >= 0; --j) { Bq = av[nn][d][j] * Bq + bv[nn][d][j]; A *= av[nn][d][j]; }
;             }
;             float Ag[4], Bg[4];
;             rowgather4(A, Ag); rowgather4(Bq, Bg);
;             float AW = 1.f, BW = 0.f, AP = 1.f, BP = 0.f;
;             if (d == 0) {
; #pragma unroll
;                 for (int g = 0; g < 4; ++g) {
;                     if (g == fq) { AP = AW; BP = BW; }
;                     BW = Ag[g] * BW + Bg[g]; AW *= Ag[g];
;                 }
;             } else {
; #pragma unroll
;                 for (int g = 3; g >= 0; --g) {
;                     if (g == fq) { AP = AW; BP = BW; }
;                     BW = Ag[g] * BW + Bg[g]; AW *= Ag[g];
;                 }
;             }
;             apre[nn][d] = AP; bpre[nn][d] = BP;
;             if (fq == 0) { wagg[((w * 2 + d) * 64 + ch) * 2 + 0] = AW; wagg[((w * 2 + d) * 64 + ch) * 2 + 1] = BW; }
	v_fmamk_f32 v62, v62, 0xbfb8aa3b, v234
	v_exp_f32_e32 v62, v62
	v_fmamk_f32 v63, v63, 0xbfb8aa3b, v234
	v_fmamk_f32 v66, v66, 0xbfb8aa3b, v235
	v_exp_f32_e32 v63, v63
	v_add_f32_e32 v62, 1.0, v62
	v_rcp_f32_e32 v62, v62
	v_exp_f32_e32 v66, v66
	v_add_f32_e32 v63, 1.0, v63
	v_rcp_f32_e32 v63, v63
	v_mul_f32_e32 v62, v255, v62
	v_add_f32_e32 v165, 1.0, v66
	v_exp_f32_e32 v66, v62
	v_rcp_f32_e32 v62, v165
	v_fmamk_f32 v67, v67, 0xbfb8aa3b, v235
	v_mul_f32_e32 v63, v255, v63
	v_fma_f32 v165, -v66, v66, 1.0
	v_sqrt_f32_e32 v165, v165
	v_exp_f32_e32 v67, v67
	v_exp_f32_e32 v63, v63
	v_fmamk_f32 v64, v64, 0xbfb8aa3b, v234
	v_exp_f32_e32 v64, v64
	v_mul_f32_e32 v62, v62, v165
	v_add_f32_e32 v67, 1.0, v67
	v_fma_f32 v165, -v63, v63, 1.0
	v_rcp_f32_e32 v67, v67
	v_sqrt_f32_e32 v165, v165
	v_add_f32_e32 v64, 1.0, v64
	v_rcp_f32_e32 v64, v64
	v_fmamk_f32 v65, v65, 0xbfb8aa3b, v234
	v_mul_f32_e32 v67, v67, v165
	v_exp_f32_e32 v165, v65
	v_mul_f32_e32 v64, v255, v64
	v_exp_f32_e32 v65, v64
	v_fmamk_f32 v68, v68, 0xbfb8aa3b, v235
	v_add_f32_e32 v64, 1.0, v165
	v_rcp_f32_e32 v64, v64
	v_fmamk_f32 v169, v69, 0xbfb8aa3b, v235
	v_exp_f32_e32 v168, v169
	v_exp_f32_e32 v68, v68
	v_mul_f32_e32 v64, v255, v64
	v_exp_f32_e32 v69, v64
	v_add_f32_e32 v64, 1.0, v168
	v_add_f32_e32 v68, 1.0, v68
	v_fma_f32 v165, -v65, v65, 1.0
	v_rcp_f32_e32 v168, v64
	v_fma_f32 v64, -v69, v69, 1.0
	v_rcp_f32_e32 v68, v68
	v_sqrt_f32_e32 v165, v165
	v_sqrt_f32_e32 v169, v64
	v_mul_f32_e32 v62, v62, v185
	v_mul_f32_e32 v64, v67, v183
	v_mul_f32_e32 v67, v68, v165
	v_mul_f32_e32 v68, v168, v169
	v_fma_f32 v168, 0, v66, v62
	v_lshlrev_b32_e32 v184, 16, v254
	v_mul_f32_e32 v67, v67, v177
	v_mul_f32_e32 v165, v66, v63
	v_fma_f32 v168, v63, v168, v64
	v_mul_f32_e32 v68, v68, v184
	v_mul_f32_e32 v165, v65, v165
	v_fma_f32 v168, v65, v168, v67
	v_mul_f32_e32 v165, v69, v165
	v_fma_f32 v168, v69, v168, v68
	v_mov_b32_e32 v171, v165
	v_mov_b32_e32 v169, v168
	s_nop 0
	v_permlane16_swap_b32_e32 v165, v171
	v_permlane16_swap_b32_e32 v168, v169
	v_mov_b32_e32 v173, v165
	v_mov_b32_e32 v170, v168
	s_nop 0
	v_permlane32_swap_b32_e32 v165, v173
	v_mov_b32_e32 v187, v171
	v_permlane32_swap_b32_e32 v168, v170
	v_mov_b32_e32 v188, v169
	v_permlane32_swap_b32_e32 v171, v187
	s_nop 0
	v_permlane32_swap_b32_e32 v169, v188
	v_fmac_f32_e32 v168, 0, v165
	v_fmac_f32_e32 v169, v168, v171
	v_mul_f32_e32 v171, v165, v171
	v_fmac_f32_e32 v170, v169, v173
	v_mul_f32_e32 v173, v171, v173
	s_and_saveexec_b64 s[28:29], s[10:11]
	v_mul_f32_e32 v189, v170, v187
	v_mul_f32_e32 v190, v173, v187
	v_add_f32_e32 v191, v189, v188
	ds_write_b64 v150, v[190:191] offset:52736
	s_or_b64 exec, exec, s[28:29]
	v_fmamk_f32 v54, v54, 0xbfb8aa3b, v236
	v_exp_f32_e32 v54, v54
	v_fmamk_f32 v55, v55, 0xbfb8aa3b, v236
	v_exp_f32_e32 v55, v55
	v_fmamk_f32 v58, v58, 0xbfb8aa3b, v237
	v_add_f32_e32 v54, 1.0, v54
	v_rcp_f32_e32 v54, v54
	v_add_f32_e32 v55, 1.0, v55
	v_exp_f32_e32 v58, v58
	v_rcp_f32_e32 v55, v55
	v_mul_f32_e32 v54, v218, v54
	v_exp_f32_e32 v54, v54
	v_fmamk_f32 v56, v56, 0xbfb8aa3b, v236
	v_fmamk_f32 v59, v59, 0xbfb8aa3b, v237
	v_add_f32_e32 v58, 1.0, v58
	v_mul_f32_e32 v55, v218, v55
	v_fma_f32 v189, -v54, v54, 1.0
	v_exp_f32_e32 v56, v56
	v_fmamk_f32 v57, v57, 0xbfb8aa3b, v236
	v_exp_f32_e32 v59, v59
	v_rcp_f32_e32 v58, v58
	v_exp_f32_e32 v55, v55
	v_sqrt_f32_e32 v189, v189
	v_exp_f32_e32 v57, v57
	v_add_f32_e32 v56, 1.0, v56
	v_add_f32_e32 v59, 1.0, v59
	v_fma_f32 v190, -v55, v55, 1.0
	v_mul_f32_e32 v58, v58, v189
	v_fmamk_f32 v60, v60, 0xbfb8aa3b, v237
	v_rcp_f32_e32 v56, v56
	v_add_f32_e32 v57, 1.0, v57
	v_rcp_f32_e32 v59, v59
	v_mul_f32_e32 v58, v58, v185
	v_sqrt_f32_e32 v185, v190
	v_exp_f32_e32 v60, v60
	v_rcp_f32_e32 v57, v57
	v_mul_f32_e32 v56, v218, v56
	v_fmamk_f32 v187, v61, 0xbfb8aa3b, v237
	v_mul_f32_e32 v185, v59, v185
	v_add_f32_e32 v59, 1.0, v60
	v_exp_f32_e32 v56, v56
	v_exp_f32_e32 v61, v187
	v_mul_f32_e32 v57, v218, v57
	v_rcp_f32_e32 v60, v59
	v_exp_f32_e32 v59, v57
	v_fma_f32 v186, -v56, v56, 1.0
	v_add_f32_e32 v57, 1.0, v61
	v_sqrt_f32_e32 v186, v186
	v_rcp_f32_e32 v61, v57
	v_fma_f32 v57, -v59, v59, 1.0
	v_sqrt_f32_e32 v187, v57
	v_mul_f32_e32 v60, v60, v186
	v_mul_f32_e32 v60, v60, v177
	v_mul_f32_e32 v177, v59, v56
	v_mul_f32_e32 v61, v61, v187
	v_mul_f32_e32 v61, v61, v184
	v_mul_f32_e32 v177, v55, v177
	v_mul_f32_e32 v186, v54, v177
	v_fma_f32 v177, 0, v59, v61
	v_mul_f32_e32 v57, v185, v183
	v_fma_f32 v177, v56, v177, v60
	v_fma_f32 v177, v55, v177, v57
	v_fma_f32 v189, v54, v177, v58
	v_mov_b32_e32 v188, v186
	v_mov_b32_e32 v177, v189
	s_nop 0
	v_permlane16_swap_b32_e32 v186, v188
	v_permlane16_swap_b32_e32 v189, v177
	v_mov_b32_e32 v183, v188
	v_mov_b32_e32 v185, v177
	v_mov_b32_e32 v187, v186
	v_permlane32_swap_b32_e32 v188, v183
	v_mov_b32_e32 v184, v189
	v_permlane32_swap_b32_e32 v177, v185
	v_permlane32_swap_b32_e32 v186, v187
	v_permlane32_swap_b32_e32 v189, v184
	v_fmac_f32_e32 v185, 0, v183
	v_fmac_f32_e32 v184, v185, v187
	v_mul_f32_e32 v187, v187, v183
	v_fmac_f32_e32 v177, v184, v188
	v_mul_f32_e32 v188, v187, v188
	s_and_saveexec_b64 s[28:29], s[10:11]
	v_mul_f32_e32 v191, v177, v186
	v_mul_f32_e32 v190, v188, v186
	v_add_f32_e32 v191, v191, v189
	ds_write_b64 v150, v[190:191] offset:53248
	s_or_b64 exec, exec, s[28:29]
	v_lshlrev_b32_e32 v197, 16, v219
	v_lshlrev_b32_e32 v195, 16, v220
	v_lshlrev_b32_e32 v194, 16, v221
	v_fmamk_f32 v46, v46, 0xbfb8aa3b, v238
	v_exp_f32_e32 v46, v46
	v_fmamk_f32 v47, v47, 0xbfb8aa3b, v238
	v_fmamk_f32 v50, v50, 0xbfb8aa3b, v239
	v_exp_f32_e32 v47, v47
	v_add_f32_e32 v46, 1.0, v46
	v_rcp_f32_e32 v46, v46
	v_exp_f32_e32 v50, v50
	v_add_f32_e32 v47, 1.0, v47
; template <bool PASS_C>
; DEVI void lru_item(const P& p, int item, int next_item, uint4& u0, uint4& u1, uint4& u2, float& cpre, char* smem) {
;     ...
;         for (int d = 0; d < 2; ++d) {
;             const float ba = prm[(5 + d) * 64 + ch], bx = prm[(7 + d) * 64 + ch], nsp8 = prm[(9 + d) * 64 + ch];
; #pragma unroll
;             for (int j = 0; j < 4; ++j) {
;                 const float r = __builtin_amdgcn_rcpf(1.0f + __builtin_amdgcn_exp2f(__builtin_fmaf(acc[(2 * d) * 4 + nn][j], -LOG2E, ba)));
;                 const float ig = __builtin_amdgcn_rcpf(1.0f + __builtin_amdgcn_exp2f(__builtin_fmaf(acc[(2 * d + 1) * 4 + nn][j], -LOG2E, bx)));
;                 const float a_ = __builtin_amdgcn_exp2f(nsp8 * r);
;                 av[nn][d][j] = a_;
;                 bv[nn][d][j] = __builtin_amdgcn_sqrtf(__builtin_fmaf(-a_, a_, 1.0f)) * ig * uc[j];
;             }
;             float A = 1.f, Bq = 0.f;
;             if (d == 0) {
; #pragma unroll
;                 for (int j = 0; j < 4; ++j) { Bq = av[nn][d][j] * Bq + bv[nn][d][j]; A *= av[nn][d][j]; }
;             } else {
; #pragma unroll
;                 for (int j = 3; j >= 0; --j) { Bq = av[nn][d][j] * Bq + bv[nn][d][j]; A *= av[nn][d][j]; }
;             }
;             float Ag[4], Bg[4];
;             rowgather4(A, Ag); rowgather4(Bq, Bg);
;             float AW = 1.f, BW = 0.f, AP = 1.f, BP = 0.f;
;             if (d == 0) {
; #pragma unroll
;                 for (int g = 0; g < 4; ++g) {
;                     if (g == fq) { AP = AW; BP = BW; }
;                     BW = Ag[g] * BW + Bg[g]; AW *= Ag[g];
;                 }
;             } else {
; #pragma unroll
;                 for (int g = 3; g >= 0; --g) {
;                     if (g == fq) { AP = AW; BP = BW; }
;                     BW = Ag[g] * BW + Bg[g]; AW *= Ag[g];
;                 }
;             }
;             apre[nn][d] = AP; bpre[nn][d] = BP;
;             if (fq == 0) { wagg[((w * 2 + d) * 64 + ch) * 2 + 0] = AW; wagg[((w * 2 + d) * 64 + ch) * 2 + 1] = BW; }
	v_rcp_f32_e32 v47, v47
	v_mul_f32_e32 v46, v223, v46
	v_add_f32_e32 v186, 1.0, v50
	v_exp_f32_e32 v50, v46
	v_rcp_f32_e32 v46, v186
	v_fmamk_f32 v51, v51, 0xbfb8aa3b, v239
	v_mul_f32_e32 v47, v223, v47
	v_fma_f32 v186, -v50, v50, 1.0
	v_sqrt_f32_e32 v186, v186
	v_exp_f32_e32 v51, v51
	v_exp_f32_e32 v47, v47
	v_fmamk_f32 v48, v48, 0xbfb8aa3b, v238
	v_exp_f32_e32 v48, v48
	v_mul_f32_e32 v46, v46, v186
	v_add_f32_e32 v51, 1.0, v51
	v_fma_f32 v186, -v47, v47, 1.0
	v_rcp_f32_e32 v51, v51
	v_sqrt_f32_e32 v186, v186
	v_add_f32_e32 v48, 1.0, v48
	v_rcp_f32_e32 v48, v48
	v_fmamk_f32 v49, v49, 0xbfb8aa3b, v238
	v_mul_f32_e32 v51, v51, v186
	v_exp_f32_e32 v186, v49
	v_mul_f32_e32 v48, v223, v48
	v_exp_f32_e32 v49, v48
	v_fmamk_f32 v52, v52, 0xbfb8aa3b, v239
	v_add_f32_e32 v48, 1.0, v186
	v_rcp_f32_e32 v48, v48
	v_fmamk_f32 v191, v53, 0xbfb8aa3b, v239
	v_exp_f32_e32 v189, v191
	v_exp_f32_e32 v52, v52
	v_mul_f32_e32 v48, v223, v48
	v_exp_f32_e32 v53, v48
	v_add_f32_e32 v48, 1.0, v189
	v_add_f32_e32 v52, 1.0, v52
	v_fma_f32 v186, -v49, v49, 1.0
	v_rcp_f32_e32 v189, v48
	v_fma_f32 v48, -v53, v53, 1.0
	v_rcp_f32_e32 v52, v52
	v_sqrt_f32_e32 v186, v186
	v_sqrt_f32_e32 v190, v48
	v_mul_f32_e32 v46, v46, v197
	v_mul_f32_e32 v48, v51, v195
	v_mul_f32_e32 v51, v52, v186
	v_mul_f32_e32 v52, v189, v190
	v_fma_f32 v189, 0, v50, v46
	v_lshlrev_b32_e32 v196, 16, v222
	v_mul_f32_e32 v51, v51, v194
	v_mul_f32_e32 v186, v50, v47
	v_fma_f32 v189, v47, v189, v48
	v_mul_f32_e32 v52, v52, v196
	v_mul_f32_e32 v186, v49, v186
	v_fma_f32 v189, v49, v189, v51
	v_mul_f32_e32 v186, v53, v186
	v_fma_f32 v189, v53, v189, v52
	v_mov_b32_e32 v192, v186
	v_mov_b32_e32 v190, v189
	s_nop 0
	v_permlane16_swap_b32_e32 v186, v192
	v_permlane16_swap_b32_e32 v189, v190
	v_mov_b32_e32 v193, v186
	v_mov_b32_e32 v191, v189
	s_nop 0
	v_permlane32_swap_b32_e32 v186, v193
	v_mov_b32_e32 v199, v192
	v_permlane32_swap_b32_e32 v189, v191
	v_mov_b32_e32 v200, v190
	v_permlane32_swap_b32_e32 v192, v199
	s_nop 0
	v_permlane32_swap_b32_e32 v190, v200
	v_fmac_f32_e32 v189, 0, v186
	v_fmac_f32_e32 v190, v189, v192
	v_mul_f32_e32 v192, v186, v192
	v_fmac_f32_e32 v191, v190, v193
	v_mul_f32_e32 v193, v192, v193
	s_and_saveexec_b64 s[28:29], s[10:11]
	v_mul_f32_e32 v201, v191, v199
	v_mul_f32_e32 v202, v193, v199
	v_add_f32_e32 v203, v201, v200
	ds_write_b64 v151, v[202:203] offset:52736
	s_or_b64 exec, exec, s[28:29]
	v_fmamk_f32 v38, v38, 0xbfb8aa3b, v240
	v_exp_f32_e32 v38, v38
	v_fmamk_f32 v39, v39, 0xbfb8aa3b, v240
	v_exp_f32_e32 v39, v39
	v_fmamk_f32 v42, v42, 0xbfb8aa3b, v241
	v_add_f32_e32 v38, 1.0, v38
	v_rcp_f32_e32 v38, v38
	v_add_f32_e32 v39, 1.0, v39
	v_exp_f32_e32 v42, v42
	v_rcp_f32_e32 v39, v39
	v_mul_f32_e32 v38, v224, v38
	v_exp_f32_e32 v38, v38
	v_fmamk_f32 v40, v40, 0xbfb8aa3b, v240
	v_fmamk_f32 v43, v43, 0xbfb8aa3b, v241
	v_add_f32_e32 v42, 1.0, v42
	v_mul_f32_e32 v39, v224, v39
	v_fma_f32 v201, -v38, v38, 1.0
	v_exp_f32_e32 v40, v40
	v_fmamk_f32 v41, v41, 0xbfb8aa3b, v240
	v_exp_f32_e32 v43, v43
	v_rcp_f32_e32 v42, v42
	v_exp_f32_e32 v39, v39
	v_sqrt_f32_e32 v201, v201
	v_exp_f32_e32 v41, v41
	v_add_f32_e32 v40, 1.0, v40
	v_add_f32_e32 v43, 1.0, v43
	v_fma_f32 v202, -v39, v39, 1.0
	v_mul_f32_e32 v42, v42, v201
	v_fmamk_f32 v44, v44, 0xbfb8aa3b, v241
	v_rcp_f32_e32 v40, v40
	v_add_f32_e32 v41, 1.0, v41
	v_rcp_f32_e32 v43, v43
	v_mul_f32_e32 v42, v42, v197
	v_sqrt_f32_e32 v197, v202
	v_exp_f32_e32 v44, v44
	v_rcp_f32_e32 v41, v41
	v_mul_f32_e32 v40, v224, v40
	v_fmamk_f32 v199, v45, 0xbfb8aa3b, v241
	v_mul_f32_e32 v197, v43, v197
	v_add_f32_e32 v43, 1.0, v44
	v_exp_f32_e32 v40, v40
	v_exp_f32_e32 v45, v199
	v_mul_f32_e32 v41, v224, v41
	v_rcp_f32_e32 v44, v43
	v_exp_f32_e32 v43, v41
	v_fma_f32 v198, -v40, v40, 1.0
	v_add_f32_e32 v41, 1.0, v45
	v_sqrt_f32_e32 v198, v198
	v_rcp_f32_e32 v45, v41
	v_fma_f32 v41, -v43, v43, 1.0
	v_sqrt_f32_e32 v199, v41
	v_mul_f32_e32 v44, v44, v198
	v_mul_f32_e32 v44, v44, v194
	v_mul_f32_e32 v194, v43, v40
	v_mul_f32_e32 v45, v45, v199
	v_mul_f32_e32 v45, v45, v196
	v_mul_f32_e32 v194, v39, v194
	v_mul_f32_e32 v198, v38, v194
	v_fma_f32 v194, 0, v43, v45
	v_mul_f32_e32 v41, v197, v195
	v_fma_f32 v194, v40, v194, v44
	v_fma_f32 v194, v39, v194, v41
	v_fma_f32 v200, v38, v194, v42
	v_mov_b32_e32 v201, v198
	v_mov_b32_e32 v194, v200
	s_nop 0
	v_permlane16_swap_b32_e32 v198, v201
	v_permlane16_swap_b32_e32 v200, v194
	v_mov_b32_e32 v195, v201
	v_mov_b32_e32 v197, v194
	v_mov_b32_e32 v199, v198
	v_permlane32_swap_b32_e32 v201, v195
	v_mov_b32_e32 v196, v200
	v_permlane32_swap_b32_e32 v194, v197
	v_permlane32_swap_b32_e32 v198, v199
	v_permlane32_swap_b32_e32 v200, v196
	v_fmac_f32_e32 v197, 0, v195
	v_fmac_f32_e32 v196, v197, v199
	v_mul_f32_e32 v199, v199, v195
	v_fmac_f32_e32 v194, v196, v201
	v_mul_f32_e32 v201, v199, v201
	s_and_saveexec_b64 s[28:29], s[10:11]
	v_mul_f32_e32 v203, v194, v198
	v_mul_f32_e32 v202, v201, v198
	v_add_f32_e32 v203, v203, v200
	ds_write_b64 v151, v[202:203] offset:53248
	s_or_b64 exec, exec, s[28:29]
	v_lshlrev_b32_e32 v209, 16, v225
	v_lshlrev_b32_e32 v207, 16, v226
	v_lshlrev_b32_e32 v206, 16, v227
	v_fmamk_f32 v30, v30, 0xbfb8aa3b, v242
	v_exp_f32_e32 v30, v30
	v_fmamk_f32 v31, v31, 0xbfb8aa3b, v242
	v_fmamk_f32 v34, v34, 0xbfb8aa3b, v243
	v_exp_f32_e32 v31, v31
	v_add_f32_e32 v30, 1.0, v30
	v_rcp_f32_e32 v30, v30
	v_exp_f32_e32 v34, v34
	v_add_f32_e32 v31, 1.0, v31
	v_rcp_f32_e32 v31, v31
	v_mul_f32_e32 v30, v229, v30
	v_add_f32_e32 v198, 1.0, v34
	v_exp_f32_e32 v34, v30
	v_rcp_f32_e32 v30, v198
	v_fmamk_f32 v35, v35, 0xbfb8aa3b, v243
	v_mul_f32_e32 v31, v229, v31
	v_fma_f32 v198, -v34, v34, 1.0
	v_sqrt_f32_e32 v198, v198
; template <bool PASS_C>
; DEVI void lru_item(const P& p, int item, int next_item, uint4& u0, uint4& u1, uint4& u2, float& cpre, char* smem) {
;     ...
;         for (int d = 0; d < 2; ++d) {
;             const float ba = prm[(5 + d) * 64 + ch], bx = prm[(7 + d) * 64 + ch], nsp8 = prm[(9 + d) * 64 + ch];
; #pragma unroll
;             for (int j = 0; j < 4; ++j) {
;                 const float r = __builtin_amdgcn_rcpf(1.0f + __builtin_amdgcn_exp2f(__builtin_fmaf(acc[(2 * d) * 4 + nn][j], -LOG2E, ba)));
;                 const float ig = __builtin_amdgcn_rcpf(1.0f + __builtin_amdgcn_exp2f(__builtin_fmaf(acc[(2 * d + 1) * 4 + nn][j], -LOG2E, bx)));
;                 const float a_ = __builtin_amdgcn_exp2f(nsp8 * r);
;                 av[nn][d][j] = a_;
;                 bv[nn][d][j] = __builtin_amdgcn_sqrtf(__builtin_fmaf(-a_, a_, 1.0f)) * ig * uc[j];
;             }
;             float A = 1.f, Bq = 0.f;
;             if (d == 0) {
; #pragma unroll
;                 for (int j = 0; j < 4; ++j) { Bq = av[nn][d][j] * Bq + bv[nn][d][j]; A *= av[nn][d][j]; }
;             } else {
; #pragma unroll
;                 for (int j = 3; j >= 0; --j) { Bq = av[nn][d][j] * Bq + bv[nn][d][j]; A *= av[nn][d][j]; }
;             }
;             float Ag[4], Bg[4];
;             rowgather4(A, Ag); rowgather4(Bq, Bg);
;             float AW = 1.f, BW = 0.f, AP = 1.f, BP = 0.f;
;             if (d == 0) {
; #pragma unroll
;                 for (int g = 0; g < 4; ++g) {
;                     if (g == fq) { AP = AW; BP = BW; }
;                     BW = Ag[g] * BW + Bg[g]; AW *= Ag[g];
;                 }
;             } else {
; #pragma unroll
;                 for (int g = 3; g >= 0; --g) {
;                     if (g == fq) { AP = AW; BP = BW; }
;                     BW = Ag[g] * BW + Bg[g]; AW *= Ag[g];
;                 }
;             }
;             apre[nn][d] = AP; bpre[nn][d] = BP;
;             if (fq == 0) { wagg[((w * 2 + d) * 64 + ch) * 2 + 0] = AW; wagg[((w * 2 + d) * 64 + ch) * 2 + 1] = BW; }
;         }
;     }
;     __syncthreads();
	v_exp_f32_e32 v35, v35
	v_exp_f32_e32 v31, v31
	v_fmamk_f32 v32, v32, 0xbfb8aa3b, v242
	v_exp_f32_e32 v32, v32
	v_mul_f32_e32 v30, v30, v198
	v_add_f32_e32 v35, 1.0, v35
	v_fma_f32 v198, -v31, v31, 1.0
	v_rcp_f32_e32 v35, v35
	v_sqrt_f32_e32 v198, v198
	v_add_f32_e32 v32, 1.0, v32
	v_rcp_f32_e32 v32, v32
	v_fmamk_f32 v33, v33, 0xbfb8aa3b, v242
	v_mul_f32_e32 v35, v35, v198
	v_exp_f32_e32 v198, v33
	v_mul_f32_e32 v32, v229, v32
	v_exp_f32_e32 v33, v32
	v_fmamk_f32 v36, v36, 0xbfb8aa3b, v243
	v_add_f32_e32 v32, 1.0, v198
	v_rcp_f32_e32 v32, v32
	v_fmamk_f32 v203, v37, 0xbfb8aa3b, v243
	v_exp_f32_e32 v200, v203
	v_exp_f32_e32 v36, v36
	v_mul_f32_e32 v32, v229, v32
	v_exp_f32_e32 v37, v32
	v_add_f32_e32 v32, 1.0, v200
	v_add_f32_e32 v36, 1.0, v36
	v_fma_f32 v198, -v33, v33, 1.0
	v_rcp_f32_e32 v200, v32
	v_fma_f32 v32, -v37, v37, 1.0
	v_rcp_f32_e32 v36, v36
	v_sqrt_f32_e32 v198, v198
	v_sqrt_f32_e32 v202, v32
	v_mul_f32_e32 v30, v30, v209
	v_mul_f32_e32 v32, v35, v207
	v_mul_f32_e32 v35, v36, v198
	v_mul_f32_e32 v36, v200, v202
	v_fma_f32 v200, 0, v34, v30
	v_lshlrev_b32_e32 v208, 16, v228
	v_mul_f32_e32 v35, v35, v206
	v_mul_f32_e32 v198, v34, v31
	v_fma_f32 v200, v31, v200, v32
	v_mul_f32_e32 v36, v36, v208
	v_mul_f32_e32 v198, v33, v198
	v_fma_f32 v200, v33, v200, v35
	v_mul_f32_e32 v198, v37, v198
	v_fma_f32 v200, v37, v200, v36
	v_mov_b32_e32 v204, v198
	v_mov_b32_e32 v202, v200
	s_nop 0
	v_permlane16_swap_b32_e32 v198, v204
	v_permlane16_swap_b32_e32 v200, v202
	v_mov_b32_e32 v205, v198
	v_mov_b32_e32 v203, v200
	s_nop 0
	v_permlane32_swap_b32_e32 v198, v205
	v_mov_b32_e32 v211, v204
	v_permlane32_swap_b32_e32 v200, v203
	v_mov_b32_e32 v212, v202
	v_permlane32_swap_b32_e32 v204, v211
	s_nop 0
	v_permlane32_swap_b32_e32 v202, v212
	v_fmac_f32_e32 v200, 0, v198
	v_fmac_f32_e32 v202, v200, v204
	v_mul_f32_e32 v204, v198, v204
	v_fmac_f32_e32 v203, v202, v205
	v_mul_f32_e32 v205, v204, v205
	s_and_saveexec_b64 s[28:29], s[10:11]
	v_mul_f32_e32 v213, v203, v211
	v_mul_f32_e32 v214, v205, v211
	v_add_f32_e32 v215, v213, v212
	ds_write_b64 v152, v[214:215] offset:52736
	s_or_b64 exec, exec, s[28:29]
	v_fmamk_f32 v22, v22, 0xbfb8aa3b, v244
	v_exp_f32_e32 v22, v22
	v_fmamk_f32 v23, v23, 0xbfb8aa3b, v244
	v_exp_f32_e32 v23, v23
	v_fmamk_f32 v26, v26, 0xbfb8aa3b, v245
	v_add_f32_e32 v22, 1.0, v22
	v_rcp_f32_e32 v22, v22
	v_add_f32_e32 v23, 1.0, v23
	v_exp_f32_e32 v26, v26
	v_rcp_f32_e32 v23, v23
	v_mul_f32_e32 v22, v231, v22
	v_exp_f32_e32 v22, v22
	v_fmamk_f32 v24, v24, 0xbfb8aa3b, v244
	v_fmamk_f32 v27, v27, 0xbfb8aa3b, v245
	v_add_f32_e32 v26, 1.0, v26
	v_mul_f32_e32 v23, v231, v23
	v_fma_f32 v213, -v22, v22, 1.0
	v_exp_f32_e32 v24, v24
	v_fmamk_f32 v25, v25, 0xbfb8aa3b, v244
	v_exp_f32_e32 v27, v27
	v_rcp_f32_e32 v26, v26
	v_exp_f32_e32 v23, v23
	v_sqrt_f32_e32 v213, v213
	v_exp_f32_e32 v25, v25
	v_add_f32_e32 v24, 1.0, v24
	v_add_f32_e32 v27, 1.0, v27
	v_fma_f32 v214, -v23, v23, 1.0
	v_mul_f32_e32 v26, v26, v213
	v_fmamk_f32 v28, v28, 0xbfb8aa3b, v245
	v_rcp_f32_e32 v24, v24
	v_add_f32_e32 v25, 1.0, v25
	v_rcp_f32_e32 v27, v27
	v_mul_f32_e32 v26, v26, v209
	v_sqrt_f32_e32 v209, v214
	v_exp_f32_e32 v28, v28
	v_rcp_f32_e32 v25, v25
	v_mul_f32_e32 v24, v231, v24
	v_fmamk_f32 v211, v29, 0xbfb8aa3b, v245
	v_mul_f32_e32 v209, v27, v209
	v_add_f32_e32 v27, 1.0, v28
	v_exp_f32_e32 v24, v24
	v_exp_f32_e32 v29, v211
	v_mul_f32_e32 v25, v231, v25
	v_rcp_f32_e32 v28, v27
	v_exp_f32_e32 v27, v25
	v_fma_f32 v210, -v24, v24, 1.0
	v_add_f32_e32 v25, 1.0, v29
	v_sqrt_f32_e32 v210, v210
	v_rcp_f32_e32 v29, v25
	v_fma_f32 v25, -v27, v27, 1.0
	v_sqrt_f32_e32 v211, v25
	v_mul_f32_e32 v28, v28, v210
	v_mul_f32_e32 v28, v28, v206
	v_mul_f32_e32 v206, v27, v24
	v_mul_f32_e32 v29, v29, v211
	v_mul_f32_e32 v29, v29, v208
	v_mul_f32_e32 v206, v23, v206
	v_mul_f32_e32 v212, v22, v206
	v_fma_f32 v206, 0, v27, v29
	v_mul_f32_e32 v25, v209, v207
	v_fma_f32 v206, v24, v206, v28
	v_fma_f32 v206, v23, v206, v25
	v_fma_f32 v213, v22, v206, v26
	v_mov_b32_e32 v211, v212
	v_mov_b32_e32 v207, v213
	s_nop 0
	v_permlane16_swap_b32_e32 v212, v211
	v_permlane16_swap_b32_e32 v213, v207
	v_mov_b32_e32 v206, v211
	v_mov_b32_e32 v209, v207
	v_mov_b32_e32 v210, v212
	v_permlane32_swap_b32_e32 v211, v206
	v_mov_b32_e32 v208, v213
	v_permlane32_swap_b32_e32 v207, v209
	v_permlane32_swap_b32_e32 v212, v210
	v_permlane32_swap_b32_e32 v213, v208
	v_fmac_f32_e32 v209, 0, v206
	v_fmac_f32_e32 v208, v209, v210
	v_mul_f32_e32 v210, v210, v206
	v_fmac_f32_e32 v207, v208, v211
	v_mul_f32_e32 v211, v210, v211
	s_and_saveexec_b64 s[28:29], s[10:11]
	v_mul_f32_e32 v214, v207, v212
	v_mul_f32_e32 v212, v211, v212
	v_add_f32_e32 v213, v214, v213
	ds_write_b64 v152, v[212:213] offset:53248
	s_or_b64 exec, exec, s[28:29]
	s_waitcnt lgkmcnt(0)
	s_barrier
; template <bool PASS_C>
; DEVI void lru_item(const P& p, int item, int next_item, uint4& u0, uint4& u1, uint4& u2, float& cpre, char* smem) {
;     ...
; #pragma unroll
;         for (int nn = 0; nn < 4; ++nn) {
;             const int ch = 16 * nn + fr;
;             float y[4];
;             {
;                 float hw = carry[ch];
; #pragma unroll
;                 for (int ww = 0; ww < 4; ++ww)
;                     if (ww < w) hw = wagg[((ww * 2 + 0) * 64 + ch) * 2] * hw + wagg[((ww * 2 + 0) * 64 + ch) * 2 + 1];
;                 float hh = apre[nn][0] * hw + bpre[nn][0];
; #pragma unroll
;                 for (int j = 0; j < 4; ++j) { hh = av[nn][0][j] * hh + bv[nn][0][j]; y[j] = hh; }
;             }
;             {
;                 float hw = carry[64 + ch];
; #pragma unroll
;     ...
;                     if (ww > w) hw = wagg[((ww * 2 + 1) * 64 + ch) * 2] * hw + wagg[((ww * 2 + 1) * 64 + ch) * 2 + 1];
;                 float hh = apre[nn][1] * hw + bpre[nn][1];
; #pragma unroll
;                 for (int j = 3; j >= 0; --j) { hh = av[nn][1][j] * hh + bv[nn][1][j]; y[j] += hh; }
;             }
; #pragma unroll
;             for (int j = 0; j < 4; ++j) ytile[(16 * w + 4 * fq + j) * 66 + ch] = y[j];
;         }
	ds_read_b32 v244, v122 offset:56832
	ds_read_b32 v245, v122 offset:57088
	ds_read_b64 v[232:233], v123 offset:52736
	ds_read_b64 v[234:235], v123 offset:53760
	ds_read_b64 v[236:237], v123 offset:54784
	ds_read_b64 v[238:239], v123 offset:56320
	ds_read_b64 v[240:241], v123 offset:55296
	ds_read_b64 v[242:243], v123 offset:54272
	ds_read_b32 v246, v122 offset:56896
	ds_read_b32 v247, v122 offset:57152
	ds_read_b64 v[218:219], v154 offset:52736
	ds_read_b64 v[220:221], v154 offset:53760
	ds_read_b64 v[222:223], v154 offset:54784
	ds_read_b64 v[224:225], v154 offset:56320
	ds_read_b64 v[226:227], v154 offset:55296
	ds_read_b64 v[228:229], v154 offset:54272
	s_waitcnt lgkmcnt(8)
	v_fma_f32 v248, v232, v244, v233
	v_cndmask_b32_e64 v212, v244, v248, s[4:5]
	v_fma_f32 v248, v234, v212, v235
	v_cndmask_b32_e64 v212, v212, v248, s[18:19]
	v_fma_f32 v248, v236, v212, v237
	v_cndmask_b32_e64 v212, v212, v248, s[20:21]
	v_fma_f32 v248, v238, v245, v239
	v_cndmask_b32_e64 v213, v245, v248, s[24:25]
	v_fma_f32 v248, v240, v213, v241
	v_cndmask_b32_e64 v213, v213, v248, s[8:9]
	v_fma_f32 v248, v242, v213, v243
	v_cndmask_b32_e64 v213, v213, v248, s[2:3]
	v_cndmask_b32_e64 v103, 1.0, v103, s[12:13]
	v_cndmask_b32_e64 v105, 0, v105, s[12:13]
	v_cndmask_b32_e64 v103, v103, v159, s[14:15]
	v_cndmask_b32_e64 v105, v105, v157, s[14:15]
	v_cndmask_b32_e64 v103, v103, v160, s[16:17]
	v_cndmask_b32_e64 v105, v105, v158, s[16:17]
	v_fmac_f32_e32 v105, v103, v212
	v_fmac_f32_e32 v87, v89, v105
	v_fmac_f32_e32 v93, v91, v87
	v_cndmask_b32_e64 v89, 1.0, v162, s[14:15]
	v_cndmask_b32_e64 v91, 0, v164, s[14:15]
	v_cndmask_b32_e64 v89, v89, v166, s[12:13]
	v_cndmask_b32_e64 v91, v91, v163, s[12:13]
	v_cndmask_b32_e64 v89, v89, v167, s[10:11]
	v_cndmask_b32_e64 v91, v91, v161, s[10:11]
	v_fmac_f32_e32 v91, v89, v213
	v_fmac_f32_e32 v77, v75, v91
	v_fmac_f32_e32 v76, v72, v77
	v_fmac_f32_e32 v73, v71, v76
	v_fmac_f32_e32 v97, v95, v93
	v_fmac_f32_e32 v74, v70, v73
	v_fmac_f32_e32 v99, v101, v97
	v_add_f32_e32 v71, v93, v73
	v_add_f32_e32 v73, v87, v74
	v_add_u32_e32 v70, 0x8c00, v153
	v_add_f32_e32 v75, v99, v77
	v_add_f32_e32 v72, v97, v76
	ds_write2_b32 v70, v73, v71 offset1:66
	ds_write2_b32 v70, v72, v75 offset0:132 offset1:198
	ds_read_b32 v244, v122 offset:56960
	ds_read_b32 v245, v122 offset:57216
	ds_read_b64 v[232:233], v155 offset:52736
	ds_read_b64 v[234:235], v155 offset:53760
	ds_read_b64 v[236:237], v155 offset:54784
	ds_read_b64 v[238:239], v155 offset:56320
	ds_read_b64 v[240:241], v155 offset:55296
	ds_read_b64 v[242:243], v155 offset:54272
	s_waitcnt lgkmcnt(10)
	v_fma_f32 v248, v218, v246, v219
	v_cndmask_b32_e64 v71, v246, v248, s[4:5]
	v_fma_f32 v248, v220, v71, v221
	v_cndmask_b32_e64 v71, v71, v248, s[18:19]
	v_fma_f32 v248, v222, v71, v223
	v_cndmask_b32_e64 v71, v71, v248, s[20:21]
	v_fma_f32 v248, v224, v247, v225
	v_cndmask_b32_e64 v72, v247, v248, s[24:25]
	v_fma_f32 v248, v226, v72, v227
	v_cndmask_b32_e64 v72, v72, v248, s[8:9]
	v_fma_f32 v248, v228, v72, v229
	v_cndmask_b32_e64 v72, v72, v248, s[2:3]
	v_cndmask_b32_e64 v73, 1.0, v165, s[12:13]
	v_cndmask_b32_e64 v74, 0, v168, s[12:13]
	v_cndmask_b32_e64 v73, v73, v171, s[14:15]
	v_cndmask_b32_e64 v74, v74, v169, s[14:15]
	v_cndmask_b32_e64 v73, v73, v173, s[16:17]
	v_cndmask_b32_e64 v74, v74, v170, s[16:17]
	v_fmac_f32_e32 v74, v73, v71
	v_fmac_f32_e32 v62, v66, v74
	v_fmac_f32_e32 v64, v63, v62
	v_fmac_f32_e32 v67, v65, v64
	v_cndmask_b32_e64 v63, 1.0, v183, s[14:15]
	v_cndmask_b32_e64 v65, 0, v185, s[14:15]
	v_cndmask_b32_e64 v63, v63, v187, s[12:13]
	v_cndmask_b32_e64 v65, v65, v184, s[12:13]
	v_cndmask_b32_e64 v63, v63, v188, s[10:11]
	v_cndmask_b32_e64 v65, v65, v177, s[10:11]
	v_fmac_f32_e32 v65, v63, v72
	v_fmac_f32_e32 v61, v59, v65
	v_fmac_f32_e32 v60, v56, v61
	v_fmac_f32_e32 v57, v55, v60
	v_fmac_f32_e32 v58, v54, v57
	v_fmac_f32_e32 v68, v69, v67
	v_add_f32_e32 v55, v64, v57
	v_add_f32_e32 v54, v62, v58
	v_add_f32_e32 v59, v68, v61
	v_add_f32_e32 v56, v67, v60
	ds_write2_b32 v70, v54, v55 offset0:16 offset1:82
	ds_write2_b32 v70, v56, v59 offset0:148 offset1:214
	ds_read_b32 v246, v122 offset:57024
	ds_read_b32 v247, v122 offset:57280
	ds_read_b64 v[218:219], v156 offset:52736
	ds_read_b64 v[220:221], v156 offset:53760
	ds_read_b64 v[222:223], v156 offset:54784
	ds_read_b64 v[224:225], v156 offset:56320
	ds_read_b64 v[226:227], v156 offset:55296
	ds_read_b64 v[228:229], v156 offset:54272
	s_waitcnt lgkmcnt(10)
	v_fma_f32 v248, v232, v244, v233
	v_cndmask_b32_e64 v54, v244, v248, s[4:5]
	v_fma_f32 v248, v234, v54, v235
	v_cndmask_b32_e64 v54, v54, v248, s[18:19]
	v_fma_f32 v248, v236, v54, v237
	v_cndmask_b32_e64 v54, v54, v248, s[20:21]
	v_fma_f32 v248, v238, v245, v239
	v_cndmask_b32_e64 v55, v245, v248, s[24:25]
	v_fma_f32 v248, v240, v55, v241
	v_cndmask_b32_e64 v55, v55, v248, s[8:9]
	v_fma_f32 v248, v242, v55, v243
	v_cndmask_b32_e64 v55, v55, v248, s[2:3]
	v_cndmask_b32_e64 v56, 1.0, v186, s[12:13]
	v_cndmask_b32_e64 v57, 0, v189, s[12:13]
	v_cndmask_b32_e64 v56, v56, v192, s[14:15]
	v_cndmask_b32_e64 v57, v57, v190, s[14:15]
	v_cndmask_b32_e64 v56, v56, v193, s[16:17]
	v_cndmask_b32_e64 v57, v57, v191, s[16:17]
	v_fmac_f32_e32 v57, v56, v54
	v_fmac_f32_e32 v46, v50, v57
	v_fmac_f32_e32 v48, v47, v46
	v_fmac_f32_e32 v51, v49, v48
	v_cndmask_b32_e64 v47, 1.0, v195, s[14:15]
	v_cndmask_b32_e64 v49, 0, v197, s[14:15]
	v_cndmask_b32_e64 v47, v47, v199, s[12:13]
	v_cndmask_b32_e64 v49, v49, v196, s[12:13]
	v_cndmask_b32_e64 v47, v47, v201, s[10:11]
	v_cndmask_b32_e64 v49, v49, v194, s[10:11]
	v_fmac_f32_e32 v49, v47, v55
	v_fmac_f32_e32 v45, v43, v49
	v_fmac_f32_e32 v44, v40, v45
	v_fmac_f32_e32 v41, v39, v44
	v_fmac_f32_e32 v42, v38, v41
	v_fmac_f32_e32 v52, v53, v51
	v_add_f32_e32 v39, v48, v41
	v_add_f32_e32 v38, v46, v42
	v_add_f32_e32 v43, v52, v45
	v_add_f32_e32 v40, v51, v44
	ds_write2_b32 v70, v38, v39 offset0:32 offset1:98
	ds_write2_b32 v70, v40, v43 offset0:164 offset1:230
	s_waitcnt lgkmcnt(2)
	v_fma_f32 v248, v218, v246, v219
	v_cndmask_b32_e64 v38, v246, v248, s[4:5]
	v_fma_f32 v248, v220, v38, v221
	v_cndmask_b32_e64 v38, v38, v248, s[18:19]
	v_fma_f32 v248, v222, v38, v223
	v_cndmask_b32_e64 v38, v38, v248, s[20:21]
	v_fma_f32 v248, v224, v247, v225
	v_cndmask_b32_e64 v39, v247, v248, s[24:25]
	v_fma_f32 v248, v226, v39, v227
	v_cndmask_b32_e64 v39, v39, v248, s[8:9]
	v_fma_f32 v248, v228, v39, v229
	v_cndmask_b32_e64 v39, v39, v248, s[2:3]
	s_branch .LBB0_720
